# baseline (speedup 1.0000x reference)
; __device__ __forceinline__ int opq(int x) { asm volatile("" : "+v"(x)); return x; }
; __device__ __forceinline__ int crow(int r, int hi) { return (r & 3) + 8 * (r >> 2) + 4 * hi; }
; __device__ __forceinline__ void attn_stream(const u16* __restrict__ Qb, const u16* __restrict__ Kh, const u16* __restrict__ Vh,
;                                             int seq, char* lds, f32x16 (&o)[4]) {
;     ...
;   if (hi == 0) li_l[r32] = l_reg;
;   asm volatile("s_waitcnt lgkmcnt(0)" ::: "memory");
; #pragma unroll
;   for (int r = 0; r < 16; ++r) { const float rl = __builtin_amdgcn_rcpf(li_l[crow(r, hi)]);
; #pragma unroll
;     for (int d0 = 0; d0 < 4; ++d0) o[d0][r] *= rl; }
; __device__ __forceinline__ void phase3(const Params& p, char* shm) {
;     ...
;     { f32x4* o1p = reinterpret_cast<f32x4*>(o1s + opq((int)threadIdx.x) * 64);
; #pragma unroll
;       for (int d0 = 0; d0 < 4; ++d0)
; #pragma unroll
;         for (int q = 0; q < 4; ++q) o1p[d0 * 4 + q] = f32x4{o[d0][q * 4], o[d0][q * 4 + 1], o[d0][q * 4 + 2], o[d0][q * 4 + 3]}; }
.LBB0_361:
	s_or_b64 exec, exec, s[6:7]
	s_and_saveexec_b64 s[0:1], s[4:5]
	ds_write_b32 v212, v192
	s_or_b64 exec, exec, s[0:1]
	s_waitcnt lgkmcnt(0)
	v_add_u32_e32 v76, v204, v190
	ds_read_b128 v[66:69], v76
	ds_read_b128 v[70:73], v76 offset:32
	s_waitcnt lgkmcnt(1)
	v_rcp_f32_e32 v66, v66
	v_rcp_f32_e32 v67, v67
	v_rcp_f32_e32 v68, v68
	v_rcp_f32_e32 v69, v69
	s_waitcnt lgkmcnt(0)
	v_rcp_f32_e32 v70, v70
	v_pk_mul_f32 v[2:3], v[2:3], v[66:67]
	v_pk_mul_f32 v[50:51], v[50:51], v[66:67]
	v_pk_mul_f32 v[34:35], v[34:35], v[66:67]
	v_pk_mul_f32 v[18:19], v[18:19], v[66:67]
	v_pk_mul_f32 v[4:5], v[4:5], v[68:69]
	v_rcp_f32_e32 v71, v71
	v_pk_mul_f32 v[52:53], v[52:53], v[68:69]
	v_pk_mul_f32 v[36:37], v[36:37], v[68:69]
	v_pk_mul_f32 v[20:21], v[20:21], v[68:69]
	ds_read_b128 v[66:69], v76 offset:64
	v_pk_mul_f32 v[6:7], v[6:7], v[70:71]
	v_pk_mul_f32 v[54:55], v[54:55], v[70:71]
	v_rcp_f32_e32 v74, v72
	v_rcp_f32_e32 v75, v73
	v_pk_mul_f32 v[38:39], v[38:39], v[70:71]
	v_pk_mul_f32 v[22:23], v[22:23], v[70:71]
	ds_read_b128 v[70:73], v76 offset:96
	s_waitcnt lgkmcnt(1)
	v_rcp_f32_e32 v66, v66
	v_rcp_f32_e32 v67, v67
	v_rcp_f32_e32 v68, v68
	v_rcp_f32_e32 v69, v69
	v_pk_mul_f32 v[40:41], v[40:41], v[74:75]
	v_pk_mul_f32 v[10:11], v[10:11], v[66:67]
	v_pk_mul_f32 v[58:59], v[58:59], v[66:67]
	v_pk_mul_f32 v[42:43], v[42:43], v[66:67]
	v_pk_mul_f32 v[26:27], v[26:27], v[66:67]
	s_waitcnt lgkmcnt(0)
	v_rcp_f32_e32 v66, v70
	v_rcp_f32_e32 v67, v71
	v_pk_mul_f32 v[12:13], v[12:13], v[68:69]
	v_pk_mul_f32 v[60:61], v[60:61], v[68:69]
	v_pk_mul_f32 v[44:45], v[44:45], v[68:69]
	v_pk_mul_f32 v[14:15], v[14:15], v[66:67]
	v_pk_mul_f32 v[62:63], v[62:63], v[66:67]
	v_pk_mul_f32 v[46:47], v[46:47], v[66:67]
	v_pk_mul_f32 v[30:31], v[30:31], v[66:67]
	v_lshrrev_b32_e32 v252, 6, v1
	v_pk_mul_f32 v[28:29], v[28:29], v[68:69]
	v_rcp_f32_e32 v68, v72
	v_rcp_f32_e32 v69, v73
	v_pk_mul_f32 v[8:9], v[8:9], v[74:75]
	v_and_b32_e32 v253, 63, v1
	v_lshlrev_b32_e32 v252, 14, v252
	v_lshl_add_u32 v252, v253, 4, v252
	v_add_u32_e32 v253, 0x1000, v252
	v_add_u32_e32 v254, 0x2000, v252
	v_add_u32_e32 v255, 0x3000, v252
	v_pk_mul_f32 v[56:57], v[56:57], v[74:75]
	v_pk_mul_f32 v[24:25], v[24:25], v[74:75]
	v_pk_mul_f32 v[16:17], v[16:17], v[68:69]
	v_pk_mul_f32 v[64:65], v[64:65], v[68:69]
	v_pk_mul_f32 v[48:49], v[48:49], v[68:69]
	v_pk_mul_f32 v[32:33], v[32:33], v[68:69]
	global_store_dwordx4 v252, v[2:5], s[16:17] nt
	global_store_dwordx4 v252, v[6:9], s[16:17] offset:1024 nt
	global_store_dwordx4 v252, v[10:13], s[16:17] offset:2048 nt
	global_store_dwordx4 v252, v[14:17], s[16:17] offset:3072 nt
	global_store_dwordx4 v253, v[50:53], s[16:17] nt
	global_store_dwordx4 v253, v[54:57], s[16:17] offset:1024 nt
	global_store_dwordx4 v253, v[58:61], s[16:17] offset:2048 nt
	global_store_dwordx4 v253, v[62:65], s[16:17] offset:3072 nt
	global_store_dwordx4 v254, v[34:37], s[16:17] nt
	global_store_dwordx4 v254, v[38:41], s[16:17] offset:1024 nt
	global_store_dwordx4 v254, v[42:45], s[16:17] offset:2048 nt
	global_store_dwordx4 v254, v[46:49], s[16:17] offset:3072 nt
	global_store_dwordx4 v255, v[18:21], s[16:17] nt
	global_store_dwordx4 v255, v[22:25], s[16:17] offset:1024 nt
	global_store_dwordx4 v255, v[26:29], s[16:17] offset:2048 nt
	global_store_dwordx4 v255, v[30:33], s[16:17] offset:3072 nt
	v_mov_b32_e32 v40, v1
	v_mov_b32_e32 v5, v191
	v_ashrrev_i32_e32 v42, 6, v40
	v_and_b32_e32 v41, 31, v40
	v_lshl_or_b32 v2, v42, 5, v41
	v_ashrrev_i32_e32 v3, 31, v2
	v_lshlrev_b64 v[2:3], 11, v[2:3]
	v_lshrrev_b32_e32 v4, 1, v40
	v_ashrrev_i32_e32 v26, 4, v40
	v_lshl_add_u64 v[2:3], s[38:39], 0, v[2:3]
	v_and_b32_e32 v190, 16, v4
	v_lshlrev_b32_e32 v50, 3, v40
	v_ashrrev_i32_e32 v27, 31, v26
	v_lshl_add_u64 v[2:3], v[2:3], 0, v[190:191]
	v_and_b32_e32 v4, 0x78, v50
	v_lshlrev_b64 v[34:35], 11, v[26:27]
	global_load_dwordx4 v[130:133], v[2:3], off offset:128
	global_load_dwordx4 v[134:137], v[2:3], off offset:160
	global_load_dwordx4 v[138:141], v[2:3], off offset:192
	global_load_dwordx4 v[142:145], v[2:3], off offset:224
	v_lshl_add_u64 v[2:3], s[34:35], 0, v[34:35]
	v_lshlrev_b32_e32 v4, 1, v4
	v_ashrrev_i32_e32 v30, 3, v40
	v_lshl_add_u64 v[38:39], v[2:3], 0, v[4:5]
	v_ashrrev_i32_e32 v31, 31, v30
	v_add_co_u32_e32 v14, vcc, s62, v38
	v_lshlrev_b32_e32 v51, 4, v40
	v_lshlrev_b64 v[36:37], 11, v[30:31]
	v_addc_co_u32_e32 v15, vcc, 0, v39, vcc
	v_and_b32_e32 v32, 0x70, v51
	v_lshl_add_u64 v[10:11], s[30:31], 0, v[36:37]
	v_mov_b32_e32 v33, v191
	v_add_co_u32_e32 v18, vcc, s63, v38
	v_add_u32_e32 v28, 32, v26
	v_lshl_add_u64 v[44:45], v[10:11], 0, v[32:33]
	v_addc_co_u32_e32 v19, vcc, 0, v39, vcc
	v_ashrrev_i32_e32 v29, 31, v28
	v_add_co_u32_e32 v22, vcc, s62, v44
	v_lshlrev_b64 v[2:3], 11, v[28:29]
	s_nop 0
	v_addc_co_u32_e32 v23, vcc, 0, v45, vcc
	v_lshl_add_u64 v[2:3], s[34:35], 0, v[2:3]
	v_add_co_u32_e32 v46, vcc, s64, v38
	v_lshl_add_u64 v[6:7], v[2:3], 0, v[4:5]
	s_nop 0
	v_addc_co_u32_e32 v47, vcc, 0, v39, vcc
	s_barrier
; __device__ __forceinline__ int v_st(int k, int c) { const int kk = (k & ~0xC) | ((k & 4) << 1) | ((k & 8) >> 1); return ((kk >> 3) * 4 + (c >> 5)) * 512 + ((kk & 7) * 32 + (c & 31)) * 2; }
; __device__ __forceinline__ int v_rd_base(int lane) { return ((lane & 3) << 3) | (((lane >> 2) & 3) << 6) | (((lane >> 4) & 1) << 5) | (((lane >> 5) & 1) << 8); }
; #define SLOAD(S, k0) do { vs##S##0 = *reinterpret_cast<const bf16x8*>(&Vh[(size_t)((k0) + sr) * LDK + sc]); \
;     vs##S##1 = *reinterpret_cast<const bf16x8*>(&Vh[(size_t)((k0) + 32 + sr) * LDK + sc]); \
;     ks##S = *reinterpret_cast<const bf16x8*>(&Kh[(size_t)((k0) + kr) * LDK + kc]); } while (0)
; #define SWRITE(b, S) do { *(bf16x8*)(V_lds + (b) * SHM_V + vst0) = vs##S##0; *(bf16x8*)(V_lds + (b) * SHM_V + vst1) = vs##S##1; \
;     *(bf16x8*)(K_lds + (b) * SHM_K + kst) = ks##S; } while (0)
; __device__ __forceinline__ void attn_stream(const u16* __restrict__ Qb, const u16* __restrict__ Kh, const u16* __restrict__ Vh,
;                                             int seq, char* lds, f32x16 (&o)[4]) {
;     ...
;   const int sr = tid >> 4, sc = (tid & 15) * 8, vst0 = v_st(sr, sc), vst1 = v_st(32 + sr, sc);
;   const int kr = tid >> 3, kc = (tid & 7) * 8, kst = KSWZ(kr, kc * 2);
;   const int vb0 = (int)(uintptr_t)(__attribute__((address_space(3))) char*)V_lds + v_rd_base(lane);
;   bf16x8 vsA0, vsA1, ksA, vsB0, vsB1, ksB;
;     ...
;   f32x16 p0, p1; float al; bf16x8 pa0, pa1, pa2, pa3; const int NT = seq / 64;
;     ...
;   const bool late = wid >= 4;
;   __syncthreads();
;   SLOAD(A, 0); SLOAD(B, 64); asm volatile("s_waitcnt vmcnt(0)" ::: "memory"); SWRITE(0, A); SWRITE(1, B);
;   SLOAD(A, 128); SLOAD(B, 192);
;   __syncthreads();
	global_load_dwordx4 v[2:5], v[38:39], off
	s_nop 0
	global_load_dwordx4 v[6:9], v[6:7], off
	s_nop 0
	global_load_dwordx4 v[10:13], v[44:45], off offset:128
	s_nop 0
	global_load_dwordx4 v[14:17], v[14:15], off
	s_nop 0
	global_load_dwordx4 v[18:21], v[18:19], off
	s_nop 0
	global_load_dwordx4 v[22:25], v[22:23], off offset:128
	v_add_co_u32_e32 v48, vcc, s65, v38
	s_waitcnt vmcnt(0)
	v_and_b32_e32 v27, 0x3fffffc0, v40
	s_nop 0
	v_addc_co_u32_e32 v49, vcc, 0, v39, vcc
	global_load_dwordx4 v[146:149], v[46:47], off
	global_load_dwordx4 v[150:153], v[48:49], off
	v_add_co_u32_e32 v46, vcc, s64, v44
	v_lshl_add_u32 v204, v27, 2, s84
	s_nop 0
	v_addc_co_u32_e32 v47, vcc, 0, v45, vcc
	v_add_co_u32_e32 v48, vcc, s66, v38
	v_and_b32_e32 v27, 0xfffff0, v26
	s_nop 0
	v_addc_co_u32_e32 v49, vcc, 0, v39, vcc
	v_add_co_u32_e32 v38, vcc, s67, v38
	global_load_dwordx4 v[158:161], v[46:47], off offset:128
	global_load_dwordx4 v[154:157], v[48:49], off
	v_addc_co_u32_e32 v39, vcc, 0, v39, vcc
	v_add_co_u32_e32 v44, vcc, s66, v44
	v_lshlrev_b32_e32 v29, 1, v26
	s_nop 0
	v_addc_co_u32_e32 v45, vcc, 0, v45, vcc
	global_load_dwordx4 v[162:165], v[38:39], off
	global_load_dwordx4 v[166:169], v[44:45], off offset:128
	v_and_or_b32 v27, v29, 8, v27
	v_lshrrev_b32_e32 v29, 1, v26
	v_lshrrev_b32_e32 v27, 1, v27
	v_bfe_u32 v31, v50, 5, 2
	v_and_b32_e32 v26, 3, v26
	v_or_b32_e32 v27, v27, v31
	v_and_or_b32 v26, v29, 4, v26
	v_lshlrev_b32_e32 v27, 9, v27
	v_lshlrev_b32_e32 v26, 6, v26
	v_and_b32_e32 v29, 48, v51
	v_or3_b32 v205, v27, v26, v29
	v_and_b32_e32 v27, 0xfffff0, v28
	v_lshlrev_b32_e32 v28, 1, v28
	v_and_or_b32 v27, v28, 8, v27
	v_lshrrev_b32_e32 v27, 1, v27
	v_or_b32_e32 v27, v27, v31
	v_lshlrev_b32_e32 v27, 9, v27
	v_or3_b32 v206, v27, v26, v29
	v_lshlrev_b32_e32 v26, 7, v30
	v_and_b32_e32 v27, 0x70, v40
	v_bitop3_b32 v26, v32, v26, v27 bitop3:0xde
	v_add_u32_e32 v27, 0, v205
	v_add_u32_e32 v207, 0, v26
	v_and_b32_e32 v43, 63, v40
	s_waitcnt vmcnt(11)
	ds_write_b128 v27, v[2:5]
	v_add_u32_e32 v2, 0, v206
	s_waitcnt vmcnt(10)
	ds_write_b128 v2, v[6:9]
	s_waitcnt vmcnt(9)
	ds_write_b128 v207, v[10:13] offset:49152
	s_waitcnt vmcnt(8)
	ds_write_b128 v27, v[14:17] offset:16384
	s_waitcnt vmcnt(7)
	ds_write_b128 v2, v[18:21] offset:16384
	s_waitcnt vmcnt(6)
	ds_write_b128 v207, v[22:25] offset:57344
	v_lshlrev_b32_e32 v2, 7, v41
	v_and_b32_e32 v3, 0x70, v50
	v_or_b32_e32 v4, 32, v190
	v_bitop3_b32 v209, v4, v2, v3 bitop3:0xde
	v_or_b32_e32 v4, 64, v190
	v_bitop3_b32 v208, v190, v2, v3 bitop3:0xde
	v_bitop3_b32 v210, v4, v2, v3 bitop3:0xde
	v_or_b32_e32 v4, 0x60, v190
	v_add_u32_e32 v6, 0, v208
	v_bitop3_b32 v211, v4, v2, v3 bitop3:0xde
	s_waitcnt lgkmcnt(0)
	s_barrier
; __device__ __forceinline__ void partialSM(f32x16& p0, f32x16& p1, float& m_reg, f32x16& negm, float& alpha, const bool first) {
;   constexpr float THR = 8.f * 1.4426950408889634f;
;   float pmax = p0[0];
; #pragma unroll
;   for (int r = 1; r < 16; ++r) pmax = fmaxf(pmax, p0[r]);
; #pragma unroll
;   for (int r = 0; r < 16; ++r) pmax = fmaxf(pmax, p1[r]);
;   { auto rr = __builtin_amdgcn_permlane32_swap(__float_as_uint(pmax), __float_as_uint(pmax), false, false);
;     pmax = fmaxf(__uint_as_float(rr[0]), __uint_as_float(rr[1])); }
;   if (__builtin_expect(!first && __all(pmax <= THR), 1)) { alpha = 1.f; }
;   else {
;     const float sh = first ? pmax : fmaxf(pmax, 0.f);
;     alpha = __builtin_amdgcn_exp2f(-sh); m_reg += sh;
; #pragma unroll
;     for (int r = 0; r < 16; ++r) { p0[r] -= sh; p1[r] -= sh; }
;     const float nm = -m_reg;
; #pragma unroll
;     for (int r = 0; r < 16; ++r) negm[r] = nm;
;   }
; #pragma unroll
;   for (int r = 0; r < 16; ++r) p0[r] = __builtin_amdgcn_exp2f(p0[r]);
; }
; __device__ __forceinline__ void finishSM(f32x16& p0, f32x16& p1, float alpha, float& l_reg, bf16x8& pa0, bf16x8& pa1, bf16x8& pa2, bf16x8& pa3) {
; #pragma unroll
;   for (int r = 0; r < 16; ++r) p1[r] = __builtin_amdgcn_exp2f(p1[r]);
;   float ps = 0;
; #pragma unroll
;   for (int r = 0; r < 16; ++r) ps += p0[r];
; #pragma unroll
;   for (int r = 0; r < 16; ++r) ps += p1[r];
;   { auto rr = __builtin_amdgcn_permlane32_swap(__float_as_uint(ps), __float_as_uint(ps), false, false);
;     ps = __uint_as_float(rr[0]) + __uint_as_float(rr[1]); }
;   l_reg = l_reg * alpha + ps;
;     ...
;   PK4(p0, 0, pa0); PK4(p0, 8, pa1); PK4(p1, 0, pa2); PK4(p1, 8, pa3);
;     ...
; }
; __device__ __forceinline__ void qkt(f32x16& p0, f32x16& p1, const char* Ks, const bf16x8* qr, int r32, int hi, const f32x16& negm) {
;     ...
;   asm volatile("s_waitcnt lgkmcnt(0)" ::: "memory");
; #pragma unroll
;   for (int d0 = 0; d0 < 4; ++d0) { asm volatile("" : "+v"(ka[d0])); asm volatile("" : "+v"(kb[d0])); }
;   SBAR();
;   p0 = __builtin_amdgcn_mfma_f32_32x32x16_bf16(ka[0], qr[0], negm, 0, 0, 0);
;   p0 = __builtin_amdgcn_mfma_f32_32x32x16_bf16(ka[1], qr[1], p0, 0, 0, 0);
;   p0 = __builtin_amdgcn_mfma_f32_32x32x16_bf16(ka[2], qr[2], p0, 0, 0, 0);
;   p0 = __builtin_amdgcn_mfma_f32_32x32x16_bf16(ka[3], qr[3], p0, 0, 0, 0);
;   p1 = __builtin_amdgcn_mfma_f32_32x32x16_bf16(kb[0], qr[0], negm, 0, 0, 0);
	v_add_u32_e32 v7, 0, v209
	v_add_u32_e32 v8, 0, v210
	v_add_u32_e32 v9, 0, v211
	ds_read_b128 v[2:5], v6 offset:49152
	ds_read_b128 v[18:21], v6 offset:53248
	ds_read_b128 v[22:25], v7 offset:49152
	ds_read_b128 v[44:47], v7 offset:53248
	ds_read_b128 v[26:29], v8 offset:49152
	ds_read_b128 v[48:51], v8 offset:53248
	ds_read_b128 v[30:33], v9 offset:49152
	ds_read_b128 v[52:55], v9 offset:53248
	s_waitcnt lgkmcnt(0)
	s_waitcnt lgkmcnt(7)
	s_waitcnt lgkmcnt(6)
	s_waitcnt lgkmcnt(5)
	s_waitcnt lgkmcnt(4)
	s_waitcnt lgkmcnt(3)
	s_waitcnt lgkmcnt(2)
	s_waitcnt lgkmcnt(1)
	s_waitcnt lgkmcnt(0)
	v_mfma_f32_32x32x16_bf16 v[2:17], v[2:5], v[130:133], 0
	v_mfma_f32_32x32x16_bf16 v[2:17], v[22:25], v[134:137], v[2:17]
	v_mfma_f32_32x32x16_bf16 v[2:17], v[26:29], v[138:141], v[2:17]
	v_mfma_f32_32x32x16_bf16 v[2:17], v[30:33], v[142:145], v[2:17]
	v_mfma_f32_32x32x16_bf16 v[18:33], v[18:21], v[130:133], 0
	v_mfma_f32_32x32x16_bf16 v[18:33], v[44:47], v[134:137], v[18:33]
	v_mfma_f32_32x32x16_bf16 v[18:33], v[48:51], v[138:141], v[18:33]
	v_mfma_f32_32x32x16_bf16 v[18:33], v[52:55], v[142:145], v[18:33]
	s_nop 7
	v_max_f32_e32 v38, v3, v3
	v_max_f32_e32 v39, v2, v2
	v_max_f32_e32 v38, v39, v38
	v_max3_f32 v38, v38, v4, v5
	v_max3_f32 v38, v38, v6, v7
	v_max3_f32 v38, v38, v8, v9
	v_max3_f32 v38, v38, v10, v11
	v_max3_f32 v38, v38, v12, v13
	v_max3_f32 v38, v38, v14, v15
	v_max3_f32 v38, v38, v16, v17
	v_max3_f32 v38, v38, v18, v19
	v_max3_f32 v38, v38, v20, v21
	v_max3_f32 v38, v38, v22, v23
	v_max3_f32 v38, v38, v24, v25
	v_max3_f32 v38, v38, v26, v27
	v_max3_f32 v38, v38, v28, v29
	v_max3_f32 v38, v38, v30, v31
	v_max3_f32 v38, v38, v32, v33
	v_mov_b32_e32 v39, v38
	s_nop 1
	v_permlane32_swap_b32_e32 v38, v39
	v_max_f32_e32 v39, v39, v39
	v_max_f32_e32 v38, v38, v38
	v_max_f32_e32 v39, v38, v39
	v_sub_f32_e32 v2, v2, v39
	v_sub_f32_e32 v3, v3, v39
	v_exp_f32_e32 v2, v2
	v_sub_f32_e32 v4, v4, v39
	v_exp_f32_e32 v3, v3
	v_sub_f32_e32 v5, v5, v39
	v_exp_f32_e32 v4, v4
	v_sub_f32_e32 v18, v18, v39
	v_sub_f32_e32 v6, v6, v39
	v_exp_f32_e32 v5, v5
	v_sub_f32_e32 v7, v7, v39
	v_exp_f32_e32 v6, v6
	v_exp_f32_e32 v38, v18
	v_add_f32_e32 v18, 0, v2
	v_sub_f32_e32 v8, v8, v39
	v_exp_f32_e32 v7, v7
	v_add_f32_e32 v18, v3, v18
	v_sub_f32_e32 v9, v9, v39
	v_exp_f32_e32 v8, v8
	v_add_f32_e32 v18, v4, v18
	v_sub_f32_e32 v10, v10, v39
	v_exp_f32_e32 v9, v9
	v_add_f32_e32 v18, v5, v18
	v_sub_f32_e32 v11, v11, v39
	v_exp_f32_e32 v10, v10
	v_add_f32_e32 v18, v6, v18
	v_sub_f32_e32 v12, v12, v39
	v_exp_f32_e32 v11, v11
	v_add_f32_e32 v18, v7, v18
	v_sub_f32_e32 v13, v13, v39
	v_exp_f32_e32 v12, v12
	v_add_f32_e32 v18, v8, v18
	v_sub_f32_e32 v14, v14, v39
	v_exp_f32_e32 v13, v13
	v_add_f32_e32 v18, v9, v18
	v_sub_f32_e32 v15, v15, v39
	v_exp_f32_e32 v14, v14
	v_add_f32_e32 v18, v10, v18
	v_sub_f32_e32 v16, v16, v39
	v_exp_f32_e32 v15, v15
	v_add_f32_e32 v18, v11, v18
	v_sub_f32_e32 v17, v17, v39
	v_exp_f32_e32 v16, v16
	v_add_f32_e32 v18, v12, v18
	v_exp_f32_e32 v17, v17
	v_add_f32_e32 v18, v13, v18
	v_sub_f32_e32 v19, v19, v39
	v_add_f32_e32 v18, v14, v18
	v_sub_f32_e32 v20, v20, v39
	v_exp_f32_e32 v45, v19
	v_add_f32_e32 v18, v15, v18
	v_sub_f32_e32 v21, v21, v39
	v_exp_f32_e32 v20, v20
	v_add_f32_e32 v18, v16, v18
	v_sub_f32_e32 v22, v22, v39
	v_exp_f32_e32 v21, v21
	v_add_f32_e32 v18, v17, v18
	v_sub_f32_e32 v23, v23, v39
	v_exp_f32_e32 v22, v22
	v_add_f32_e32 v18, v38, v18
	v_sub_f32_e32 v24, v24, v39
	v_exp_f32_e32 v23, v23
	v_add_f32_e32 v18, v45, v18
	v_sub_f32_e32 v25, v25, v39
	v_exp_f32_e32 v24, v24
	v_add_f32_e32 v18, v20, v18
	v_sub_f32_e32 v26, v26, v39
	v_exp_f32_e32 v25, v25
	v_add_f32_e32 v18, v21, v18
	v_sub_f32_e32 v27, v27, v39
	v_exp_f32_e32 v26, v26
	v_add_f32_e32 v18, v22, v18
	v_sub_f32_e32 v28, v28, v39
	v_exp_f32_e32 v27, v27
	v_add_f32_e32 v18, v23, v18
	v_sub_f32_e32 v29, v29, v39
	v_exp_f32_e32 v28, v28
	v_add_f32_e32 v18, v24, v18
	v_sub_f32_e32 v30, v30, v39
	v_exp_f32_e32 v29, v29
	v_add_f32_e32 v18, v25, v18
	v_sub_f32_e32 v31, v31, v39
	v_exp_f32_e32 v30, v30
	v_add_f32_e32 v18, v26, v18
	v_sub_f32_e32 v32, v32, v39
	v_exp_f32_e32 v31, v31
	v_add_f32_e32 v18, v27, v18
	v_sub_f32_e32 v33, v33, v39
	v_exp_f32_e32 v32, v32
	v_add_f32_e32 v18, v28, v18
	v_exp_f32_e32 v33, v33
	v_add_f32_e32 v18, v29, v18
	v_add_f32_e32 v18, v30, v18
	v_exp_f32_e64 v44, -v39
	v_add_f32_e32 v18, v31, v18
	v_add_f32_e32 v18, v32, v18
	v_add_f32_e32 v18, v33, v18
	v_mov_b32_e32 v19, v18
	s_nop 0
	v_cvt_pk_bf16_f32 v170, v2, v3
	s_nop 0
	v_cvt_pk_bf16_f32 v171, v4, v5
	s_nop 0
	v_cvt_pk_bf16_f32 v172, v6, v7
	s_nop 0
	v_cvt_pk_bf16_f32 v173, v8, v9
	s_nop 0
	v_cvt_pk_bf16_f32 v174, v10, v11
	s_nop 0
	v_cvt_pk_bf16_f32 v175, v12, v13
	s_nop 0
	v_cvt_pk_bf16_f32 v176, v14, v15
	s_nop 0
	v_cvt_pk_bf16_f32 v177, v16, v17
	s_nop 0
	v_cvt_pk_bf16_f32 v178, v38, v45
	s_nop 0
	v_cvt_pk_bf16_f32 v179, v20, v21
	s_nop 0
	v_cvt_pk_bf16_f32 v180, v22, v23
	s_nop 0
	v_cvt_pk_bf16_f32 v181, v24, v25
	s_nop 0
	v_cvt_pk_bf16_f32 v182, v26, v27
	s_nop 0
	v_cvt_pk_bf16_f32 v183, v28, v29
	s_nop 0
	v_cvt_pk_bf16_f32 v184, v30, v31
	s_nop 0
	v_cvt_pk_bf16_f32 v185, v32, v33
	s_nop 1
	v_permlane32_swap_b32_e32 v18, v19
	v_permlane32_swap_b32_e32 v170, v172
	v_permlane32_swap_b32_e32 v171, v173
	v_permlane32_swap_b32_e32 v174, v176
	v_permlane32_swap_b32_e32 v175, v177
	v_permlane32_swap_b32_e32 v178, v180
	v_permlane32_swap_b32_e32 v179, v181
	v_permlane32_swap_b32_e32 v182, v184
	v_permlane32_swap_b32_e32 v183, v185
	v_cmp_gt_f32_e32 vcc, 1.0, v44
	v_cmp_gt_u32_e64 s[0:1], 32, v43
	s_cbranch_vccz .LBB0_367
	s_and_saveexec_b64 s[4:5], s[0:1]
	v_lshl_add_u32 v2, v41, 2, v204
	ds_write_b32 v2, v44 offset:128
	s_or_b64 exec, exec, s[4:5]
	s_waitcnt lgkmcnt(0)
	v_add_u32_e32 v10, v204, v190
	ds_read_b128 v[2:5], v10 offset:224
	ds_read_b128 v[6:9], v10 offset:192
	ds_read_b128 v[20:23], v10 offset:160
	ds_read_b128 v[24:27], v10 offset:128
	s_waitcnt lgkmcnt(3)
	v_pk_mul_f32 v[16:17], v[4:5], 0 op_sel_hi:[1,0]
	s_waitcnt lgkmcnt(2)
	v_pk_mul_f32 v[12:13], v[8:9], 0 op_sel_hi:[1,0]
	s_waitcnt lgkmcnt(1)
	v_pk_mul_f32 v[8:9], v[22:23], 0 op_sel_hi:[1,0]
	s_waitcnt lgkmcnt(0)
	v_pk_mul_f32 v[4:5], v[26:27], 0 op_sel_hi:[1,0]
	v_pk_mul_f32 v[14:15], v[2:3], 0 op_sel_hi:[1,0]
	v_pk_mul_f32 v[10:11], v[6:7], 0 op_sel_hi:[1,0]
	v_pk_mul_f32 v[6:7], v[20:21], 0 op_sel_hi:[1,0]
	v_pk_mul_f32 v[2:3], v[24:25], 0 op_sel_hi:[1,0]
	s_branch .LBB0_368

; __device__ __forceinline__ int crow(int r, int hi) { return (r & 3) + 8 * (r >> 2) + 4 * hi; }
; __device__ __forceinline__ void attn_stream(const u16* __restrict__ Qb, const u16* __restrict__ Kh, const u16* __restrict__ Vh,
;                                             int seq, char* lds, f32x16 (&o)[4]) {
;     ...
;   if (hi == 0) li_l[r32] = l_reg;
;   asm volatile("s_waitcnt lgkmcnt(0)" ::: "memory");
; #pragma unroll
;   for (int r = 0; r < 16; ++r) { const float rl = __builtin_amdgcn_rcpf(li_l[crow(r, hi)]);
; #pragma unroll
;     for (int d0 = 0; d0 < 4; ++d0) o[d0][r] *= rl; }
; __device__ __forceinline__ void phase3(const Params& p, char* shm) {
;     ...
;     { const f32x4* o1p = reinterpret_cast<const f32x4*>(o1s + tid * 64);
; #pragma unroll
;       for (int d0 = 0; d0 < 4; ++d0)
; #pragma unroll
;         for (int q = 0; q < 4; ++q) { const f32x4 v1 = o1p[d0 * 4 + q];
; #pragma unroll
;           for (int e = 0; e < 4; ++e) o[d0][q * 4 + e] = v1[e] - lam * o[d0][q * 4 + e]; } }
;     float sw[4];
; #pragma unroll
;     for (int d0 = 0; d0 < 4; ++d0) sw[d0] = p.subln[d0 * 32 + r32] * 0.8f;
.LBB0_401:
	s_or_b64 exec, exec, s[6:7]
	s_and_saveexec_b64 s[0:1], s[4:5]
	ds_write_b32 v212, v192
	s_or_b64 exec, exec, s[0:1]
	s_waitcnt lgkmcnt(0)
	v_add_u32_e32 v66, v204, v190
	v_mov_b32_e32 v131, v1
	ds_read_b128 v[138:141], v66
	s_waitcnt vmcnt(2)
	ds_read_b128 v[144:147], v66 offset:32
	s_waitcnt vmcnt(1)
	ds_read_b128 v[148:151], v66 offset:64
	ds_read_b128 v[152:155], v66 offset:96
	s_waitcnt lgkmcnt(0)
	s_barrier
	v_mov_b32_e32 v156, v2
	v_lshrrev_b32_e32 v252, 6, v131
	v_and_b32_e32 v253, 63, v131
	v_lshlrev_b32_e32 v252, 14, v252
	v_lshl_add_u32 v252, v253, 4, v252
	v_add_u32_e32 v253, 0x1000, v252
	v_add_u32_e32 v254, 0x2000, v252
	v_add_u32_e32 v255, 0x3000, v252
	global_load_dwordx4 v[118:121], v252, s[16:17] nt
	global_load_dwordx4 v[126:129], v253, s[16:17] nt
	global_load_dwordx4 v[114:117], v254, s[16:17] nt
	global_load_dwordx4 v[122:125], v255, s[16:17] nt
	global_load_dwordx4 v[110:113], v252, s[16:17] offset:1024 nt
	global_load_dwordx4 v[106:109], v253, s[16:17] offset:1024 nt
	global_load_dwordx4 v[102:105], v254, s[16:17] offset:1024 nt
	global_load_dwordx4 v[98:101], v255, s[16:17] offset:1024 nt
	v_and_b32_e32 v143, 31, v131
	v_lshlrev_b32_e32 v68, 2, v143
	global_load_dword v161, v68, s[14:15]
	global_load_dword v163, v68, s[14:15] offset:128
	v_and_b32_e32 v67, 64, v203
	v_xor_b32_e32 v66, 1, v203
	v_add_u32_e32 v2, 64, v67
	v_xor_b32_e32 v69, 2, v203
	v_cmp_lt_i32_e32 vcc, v66, v2
	v_xor_b32_e32 v70, 4, v203
	s_waitcnt vmcnt(10)
	v_mov_b32_e32 v159, v18
	v_mov_b32_e32 v18, v35
	v_cndmask_b32_e32 v35, v203, v66, vcc
	v_cmp_lt_i32_e32 vcc, v69, v2
	global_load_dword v165, v68, s[14:15] offset:256
	global_load_dword v168, v68, s[14:15] offset:384
	v_xor_b32_e32 v68, 8, v203
	v_cndmask_b32_e32 v66, v203, v69, vcc
	v_cmp_lt_i32_e32 vcc, v70, v2
	v_xor_b32_e32 v71, 16, v203
	v_mov_b32_e32 v157, v50
	v_cndmask_b32_e32 v67, v203, v70, vcc
	v_cmp_lt_i32_e32 vcc, v68, v2
	v_mov_b32_e32 v50, v3
	v_lshrrev_b32_e32 v3, 3, v131
	v_cndmask_b32_e32 v68, v203, v68, vcc
	v_cmp_lt_i32_e32 vcc, v71, v2
	v_mov_b32_e32 v158, v34
	v_lshrrev_b32_e32 v34, 1, v131
	v_cndmask_b32_e32 v2, v203, v71, vcc
	v_and_b32_e32 v69, 4, v3
	v_lshlrev_b32_e32 v3, 2, v2
	v_and_or_b32 v2, v34, s69, v69
	v_mul_lo_u32 v169, v2, s70
	v_rcp_f32_e32 v2, v138
	v_rcp_f32_e32 v162, v140
	v_rcp_f32_e32 v140, v146
	v_rcp_f32_e32 v138, v147
	v_pk_mul_f32 v[146:147], v[156:157], v[2:3] op_sel_hi:[1,0]
	v_pk_mul_f32 v[156:157], v[158:159], v[2:3] op_sel_hi:[1,0]
	v_lshlrev_b32_e32 v137, 2, v35
	v_lshlrev_b32_e32 v135, 2, v66
	v_lshlrev_b32_e32 v133, 2, v67
	v_lshlrev_b32_e32 v35, 2, v68
	v_rcp_f32_e32 v164, v141
	v_rcp_f32_e32 v160, v139
	v_or_b32_e32 v139, v169, v143
	v_rcp_f32_e32 v136, v148
	v_rcp_f32_e32 v134, v149
	v_rcp_f32_e32 v132, v150
	v_rcp_f32_e32 v130, v151
	global_load_dwordx4 v[74:77], v252, s[16:17] offset:3072 nt
	global_load_dwordx4 v[90:93], v252, s[16:17] offset:2048 nt
	global_load_dwordx4 v[78:81], v253, s[16:17] offset:3072 nt
	global_load_dwordx4 v[94:97], v253, s[16:17] offset:2048 nt
	global_load_dwordx4 v[66:69], v254, s[16:17] offset:3072 nt
	global_load_dwordx4 v[82:85], v254, s[16:17] offset:2048 nt
	global_load_dwordx4 v[70:73], v255, s[16:17] offset:3072 nt
	s_nop 0
	global_load_dwordx4 v[86:89], v255, s[16:17] offset:2048 nt
	v_rcp_f32_e32 v144, v144
	v_rcp_f32_e32 v142, v145
	s_waitcnt vmcnt(19)
	v_mov_b32_e32 v158, v118
	s_waitcnt vmcnt(18)
	v_mov_b32_e32 v159, v126
	s_waitcnt vmcnt(17)
	v_mov_b32_e32 v166, v114
	s_waitcnt vmcnt(16)
	v_mov_b32_e32 v167, v122
	v_pk_fma_f32 v[146:147], v[188:189], v[146:147], v[158:159] neg_lo:[1,0,0] neg_hi:[1,0,0]
	v_pk_fma_f32 v[156:157], v[188:189], v[156:157], v[166:167] neg_lo:[1,0,0] neg_hi:[1,0,0]
	v_pk_mul_f32 v[158:159], v[146:147], v[146:147]
	v_pk_mul_f32 v[166:167], v[156:157], v[156:157]
	v_add_f32_e32 v2, v158, v159
	v_add_f32_e32 v2, v2, v166
	v_add_f32_e32 v2, v2, v167
	s_nop 1
	v_mov_b32_dpp v34, v2 quad_perm:[1,0,3,2] row_mask:0xf bank_mask:0xf
	s_waitcnt vmcnt(11)
	v_pk_mul_f32 v[148:149], v[50:51], v[160:161] op_sel_hi:[1,0]
	v_pk_mul_f32 v[150:151], v[18:19], v[160:161] op_sel_hi:[1,0]
	v_mul_f32_e32 v51, 0x3f4ccccd, v161
	v_rcp_f32_e32 v118, v152
	s_waitcnt lgkmcnt(0)
	v_add_f32_e32 v122, v2, v34
	s_nop 1
	v_mov_b32_dpp v126, v122 quad_perm:[2,3,0,1] row_mask:0xf bank_mask:0xf
	v_rcp_f32_e32 v114, v153
	v_mov_b32_e32 v152, v116
	v_mov_b32_e32 v153, v124
	s_waitcnt vmcnt(10)
	v_mul_f32_e32 v50, 0x3f4ccccd, v163
	s_waitcnt lgkmcnt(0)
	v_add_f32_e32 v122, v122, v126
	s_nop 1
	v_mov_b32_dpp v126, v122 row_half_mirror row_mask:0xf bank_mask:0xf
	s_waitcnt vmcnt(9)
	v_mul_f32_e32 v19, 0x3f4ccccd, v165
	s_waitcnt vmcnt(8)
	v_mul_f32_e32 v18, 0x3f4ccccd, v168
	v_mov_b32_e32 v124, v117
	v_mov_b32_e32 v117, v22
	s_waitcnt lgkmcnt(0)
	v_add_f32_e32 v141, v122, v126
	s_nop 1
	v_mov_b32_dpp v143, v141 row_mirror row_mask:0xf bank_mask:0xf
	v_mov_b32_e32 v122, v115
	v_mov_b32_e32 v126, v119
	v_pk_fma_f32 v[126:127], v[188:189], v[148:149], v[126:127] neg_lo:[1,0,0] neg_hi:[1,0,0]
	v_pk_fma_f32 v[122:123], v[188:189], v[150:151], v[122:123] neg_lo:[1,0,0] neg_hi:[1,0,0]
	s_waitcnt lgkmcnt(0)
	v_add_f32_e32 v115, v141, v143
	ds_bpermute_b32 v119, v3, v115
	v_pk_mul_f32 v[148:149], v[126:127], v[126:127]
	v_pk_mul_f32 v[150:151], v[122:123], v[122:123]
	v_rcp_f32_e32 v34, v154
	v_rcp_f32_e32 v2, v155
	s_waitcnt lgkmcnt(0)
	v_add_f32_e32 v115, v115, v119
	v_add_f32_e32 v119, v148, v149
	v_add_f32_e32 v119, v119, v150
	v_add_f32_e32 v119, v119, v151
	v_fmamk_f32 v115, v115, 0x3c000000, v187
	s_nop 1
	v_mov_b32_dpp v141, v119 quad_perm:[1,0,3,2] row_mask:0xf bank_mask:0xf
	v_mul_f32_e32 v143, 0x4b800000, v115
	v_cmp_gt_f32_e32 vcc, s71, v115
	v_mov_b32_e32 v148, v120
	v_mov_b32_e32 v149, v128
	v_cndmask_b32_e32 v115, v115, v143, vcc
	v_rsq_f32_e32 v143, v115
	s_waitcnt lgkmcnt(0)
; __device__ __forceinline__ u16 f2bf(float f) { return (u16)(cvtpk(f, f) & 0xffffu); }
; __device__ __forceinline__ void phase3(const Params& p, char* shm) {
;     ...
;     for (int r = 0; r < 16; ++r) {
;       float ss = 0.f;
; #pragma unroll
;       for (int d0 = 0; d0 < 4; ++d0) ss += o[d0][r] * o[d0][r];
;       ss += __shfl_xor(ss, 1); ss += __shfl_xor(ss, 2); ss += __shfl_xor(ss, 4); ss += __shfl_xor(ss, 8); ss += __shfl_xor(ss, 16);
;       const float rstd = rsqrtf(ss * (1.f / 128.f) + 1e-6f);
; #pragma unroll
;       for (int d0 = 0; d0 < 4; ++d0) *(u16*)(otb + (((r & 3) + 8 * (r >> 2)) * OT_LD + d0 * 32) * 2) = f2bf(o[d0][r] * rstd * sw[d0]);
;     }
	v_add_f32_e32 v119, v119, v141
	s_nop 1
	v_mov_b32_dpp v141, v119 quad_perm:[2,3,0,1] row_mask:0xf bank_mask:0xf
	v_lshl_add_u32 v115, v139, 1, 0
	v_mul_f32_e32 v139, 0x45800000, v143
	v_cndmask_b32_e32 v139, v143, v139, vcc
	v_mul_f32_e32 v143, v146, v139
	v_mul_f32_e32 v143, v51, v143
	s_waitcnt lgkmcnt(0)
	v_add_f32_e32 v119, v119, v141
	s_nop 0
	v_cvt_pk_bf16_f32 v143, v143, v143
	s_nop 1
	v_mov_b32_dpp v141, v119 row_half_mirror row_mask:0xf bank_mask:0xf
	ds_write_b16 v115, v143
	v_mul_f32_e32 v143, v147, v139
	v_mov_b32_e32 v146, v4
	v_mov_b32_e32 v147, v52
	v_pk_mul_f32 v[146:147], v[146:147], v[162:163] op_sel_hi:[1,0]
	v_mov_b32_e32 v150, v36
	v_mov_b32_e32 v151, v20
	v_pk_fma_f32 v[146:147], v[188:189], v[146:147], v[148:149] neg_lo:[1,0,0] neg_hi:[1,0,0]
	v_pk_mul_f32 v[150:151], v[150:151], v[162:163] op_sel_hi:[1,0]
	v_pk_mul_f32 v[148:149], v[146:147], v[146:147]
	v_pk_fma_f32 v[150:151], v[188:189], v[150:151], v[152:153] neg_lo:[1,0,0] neg_hi:[1,0,0]
	v_add_f32_e32 v4, v148, v149
	v_pk_mul_f32 v[152:153], v[150:151], v[150:151]
	s_waitcnt lgkmcnt(1)
	v_add_f32_e32 v119, v119, v141
	v_add_f32_e32 v4, v4, v152
	s_nop 1
	v_mov_b32_dpp v141, v119 row_mirror row_mask:0xf bank_mask:0xf
	v_add_f32_e32 v4, v4, v153
	s_nop 1
	v_mov_b32_dpp v20, v4 quad_perm:[1,0,3,2] row_mask:0xf bank_mask:0xf
	v_mul_f32_e32 v143, v50, v143
	s_nop 0
	v_cvt_pk_bf16_f32 v143, v143, v143
	s_waitcnt lgkmcnt(0)
	v_add_f32_e32 v119, v119, v141
	ds_bpermute_b32 v141, v3, v119
	s_waitcnt lgkmcnt(1)
	v_add_f32_e32 v4, v4, v20
	s_nop 1
	v_mov_b32_dpp v20, v4 quad_perm:[2,3,0,1] row_mask:0xf bank_mask:0xf
	ds_write_b16 v115, v143 offset:64
	v_mul_f32_e32 v143, v156, v139
	s_waitcnt lgkmcnt(1)
	v_add_f32_e32 v119, v119, v141
	v_fmamk_f32 v119, v119, 0x3c000000, v187
	s_waitcnt lgkmcnt(1)
	v_add_f32_e32 v4, v4, v20
	v_mul_f32_e32 v141, 0x4b800000, v119
	v_cmp_gt_f32_e32 vcc, s71, v119
	s_nop 1
	v_mov_b32_dpp v20, v4 row_half_mirror row_mask:0xf bank_mask:0xf
	v_mul_f32_e32 v139, v157, v139
	v_cndmask_b32_e32 v119, v119, v141, vcc
	v_rsq_f32_e32 v119, v119
	v_mul_f32_e32 v143, v19, v143
	v_mul_f32_e32 v36, v18, v139
	s_nop 0
	v_cvt_pk_bf16_f32 v143, v143, v143
	ds_write_b16 v115, v143 offset:128
	s_nop 0
	v_cvt_pk_bf16_f32 v36, v36, v36
	s_waitcnt lgkmcnt(1)
	v_add_f32_e32 v4, v4, v20
	ds_write_b16 v115, v36 offset:192
	v_mul_f32_e32 v36, 0x45800000, v119
	s_nop 1
	v_mov_b32_dpp v20, v4 row_mirror row_mask:0xf bank_mask:0xf
	v_cndmask_b32_e32 v36, v119, v36, vcc
	v_mul_f32_e32 v52, v126, v36
	v_mul_f32_e32 v52, v51, v52
	s_nop 0
	v_cvt_pk_bf16_f32 v52, v52, v52
	ds_write_b16 v115, v52 offset:272
	v_mul_f32_e32 v52, v127, v36
	s_waitcnt lgkmcnt(1)
	v_add_f32_e32 v4, v4, v20
	v_mul_f32_e32 v52, v50, v52
	ds_bpermute_b32 v20, v3, v4
	s_nop 0
	v_cvt_pk_bf16_f32 v52, v52, v52
	ds_write_b16 v115, v52 offset:336
	v_mul_f32_e32 v52, v122, v36
	v_mul_f32_e32 v52, v19, v52
	s_nop 0
	v_cvt_pk_bf16_f32 v52, v52, v52
	ds_write_b16 v115, v52 offset:400
	s_waitcnt lgkmcnt(2)
	v_add_f32_e32 v4, v4, v20
	v_mov_b32_e32 v52, v5
	v_fmamk_f32 v119, v4, 0x3c000000, v187
	v_pk_mul_f32 v[4:5], v[52:53], v[164:165] op_sel_hi:[1,0]
	v_mov_b32_e32 v128, v121
	v_mov_b32_e32 v20, v37
	v_mul_f32_e32 v36, v123, v36
	v_pk_fma_f32 v[4:5], v[188:189], v[4:5], v[128:129] neg_lo:[1,0,0] neg_hi:[1,0,0]
	v_pk_mul_f32 v[20:21], v[20:21], v[164:165] op_sel_hi:[1,0]
	v_mul_f32_e32 v36, v18, v36
	v_pk_mul_f32 v[52:53], v[4:5], v[4:5]
	v_pk_fma_f32 v[20:21], v[188:189], v[20:21], v[124:125] neg_lo:[1,0,0] neg_hi:[1,0,0]
	s_nop 0
	v_cvt_pk_bf16_f32 v116, v36, v36
	v_add_f32_e32 v52, v52, v53
	v_pk_mul_f32 v[36:37], v[20:21], v[20:21]
	v_cmp_gt_f32_e32 vcc, s71, v119
	v_add_f32_e32 v36, v52, v36
	v_add_f32_e32 v36, v36, v37
	s_nop 1
	v_mov_b32_dpp v37, v36 quad_perm:[1,0,3,2] row_mask:0xf bank_mask:0xf
	v_mul_f32_e32 v52, 0x4b800000, v119
	v_cndmask_b32_e32 v52, v119, v52, vcc
	v_rsq_f32_e32 v52, v52
	ds_write_b16 v115, v116 offset:464
	s_waitcnt lgkmcnt(1)
	v_add_f32_e32 v36, v36, v37
	s_nop 1
	v_mov_b32_dpp v37, v36 quad_perm:[2,3,0,1] row_mask:0xf bank_mask:0xf
	v_mul_f32_e32 v53, 0x45800000, v52
	v_cndmask_b32_e32 v52, v52, v53, vcc
	v_mul_f32_e32 v53, v146, v52
	v_mul_f32_e32 v53, v51, v53
	s_waitcnt lgkmcnt(0)
	v_add_f32_e32 v36, v36, v37
	s_nop 1
	v_mov_b32_dpp v37, v36 row_half_mirror row_mask:0xf bank_mask:0xf
	s_nop 0
	v_cvt_pk_bf16_f32 v53, v53, v53
	ds_write_b16 v115, v53 offset:544
	v_mul_f32_e32 v53, v147, v52
	v_mul_f32_e32 v53, v50, v53
	s_waitcnt lgkmcnt(1)
	v_add_f32_e32 v36, v36, v37
	s_nop 1
	v_mov_b32_dpp v37, v36 row_mirror row_mask:0xf bank_mask:0xf
	s_nop 0
	v_cvt_pk_bf16_f32 v53, v53, v53
	ds_write_b16 v115, v53 offset:608
	v_mul_f32_e32 v53, v150, v52
	v_mul_f32_e32 v53, v19, v53
	s_waitcnt lgkmcnt(1)
	v_add_f32_e32 v36, v36, v37
	ds_bpermute_b32 v37, v3, v36
	s_nop 0
	v_cvt_pk_bf16_f32 v53, v53, v53
	ds_write_b16 v115, v53 offset:672
	v_mul_f32_e32 v119, v151, v52
	v_mov_b32_e32 v52, v110
	s_waitcnt lgkmcnt(1)
	v_add_f32_e32 v36, v36, v37
	v_fmamk_f32 v36, v36, 0x3c000000, v187
	v_mul_f32_e32 v37, 0x4b800000, v36
	v_cmp_gt_f32_e32 vcc, s71, v36
	v_mov_b32_e32 v53, v106
	v_mov_b32_e32 v116, v38
	v_cndmask_b32_e32 v36, v36, v37, vcc
	v_rsq_f32_e32 v122, v36
	v_mov_b32_e32 v36, v6
	v_mov_b32_e32 v37, v54
	v_pk_mul_f32 v[36:37], v[36:37], v[144:145] op_sel_hi:[1,0]
	v_pk_mul_f32 v[116:117], v[116:117], v[144:145] op_sel_hi:[1,0]
	v_pk_fma_f32 v[36:37], v[188:189], v[36:37], v[52:53] neg_lo:[1,0,0] neg_hi:[1,0,0]
	v_mov_b32_e32 v120, v102
	v_mov_b32_e32 v121, v98
	v_pk_mul_f32 v[52:53], v[36:37], v[36:37]
	v_pk_fma_f32 v[116:117], v[188:189], v[116:117], v[120:121] neg_lo:[1,0,0] neg_hi:[1,0,0]
	v_add_f32_e32 v6, v52, v53
	v_pk_mul_f32 v[120:121], v[116:117], v[116:117]
	v_mul_f32_e32 v38, v18, v119
	v_add_f32_e32 v6, v6, v120
	v_add_f32_e32 v6, v6, v121
	s_nop 1
	v_mov_b32_dpp v22, v6 quad_perm:[1,0,3,2] row_mask:0xf bank_mask:0xf
	s_nop 0
	v_cvt_pk_bf16_f32 v38, v38, v38
	ds_write_b16 v115, v38 offset:736
	v_mul_f32_e32 v38, 0x45800000, v122
	v_cndmask_b32_e32 v38, v122, v38, vcc
	s_waitcnt lgkmcnt(1)
; __device__ __forceinline__ u16 f2bf(float f) { return (u16)(cvtpk(f, f) & 0xffffu); }
; __device__ __forceinline__ void phase3(const Params& p, char* shm) {
;     ...
;     { const f32x4* o1p = reinterpret_cast<const f32x4*>(o1s + tid * 64);
; #pragma unroll
;       for (int d0 = 0; d0 < 4; ++d0)
; #pragma unroll
;         for (int q = 0; q < 4; ++q) { const f32x4 v1 = o1p[d0 * 4 + q];
; #pragma unroll
;           for (int e = 0; e < 4; ++e) o[d0][q * 4 + e] = v1[e] - lam * o[d0][q * 4 + e]; } }
;     float sw[4];
; #pragma unroll
;     for (int d0 = 0; d0 < 4; ++d0) sw[d0] = p.subln[d0 * 32 + r32] * 0.8f;
;     char* const otb = shm + ((wid * 32 + 4 * hi) * OT_LD + r32) * 2;
; #pragma unroll
;     for (int r = 0; r < 16; ++r) {
;       float ss = 0.f;
; #pragma unroll
;       for (int d0 = 0; d0 < 4; ++d0) ss += o[d0][r] * o[d0][r];
;       ss += __shfl_xor(ss, 1); ss += __shfl_xor(ss, 2); ss += __shfl_xor(ss, 4); ss += __shfl_xor(ss, 8); ss += __shfl_xor(ss, 16);
;       const float rstd = rsqrtf(ss * (1.f / 128.f) + 1e-6f);
; #pragma unroll
;       for (int d0 = 0; d0 < 4; ++d0) *(u16*)(otb + (((r & 3) + 8 * (r >> 2)) * OT_LD + d0 * 32) * 2) = f2bf(o[d0][r] * rstd * sw[d0]);
;     }
	v_add_f32_e32 v6, v6, v22
	s_nop 1
	v_mov_b32_dpp v22, v6 quad_perm:[2,3,0,1] row_mask:0xf bank_mask:0xf
	v_mul_f32_e32 v4, v4, v38
	v_mul_f32_e32 v4, v51, v4
	s_nop 0
	v_cvt_pk_bf16_f32 v4, v4, v4
	ds_write_b16 v115, v4 offset:816
	s_waitcnt lgkmcnt(1)
	v_add_f32_e32 v6, v6, v22
	s_nop 1
	v_mov_b32_dpp v22, v6 row_half_mirror row_mask:0xf bank_mask:0xf
	v_mul_f32_e32 v4, v5, v38
	v_mul_f32_e32 v4, v50, v4
	s_nop 0
	v_cvt_pk_bf16_f32 v4, v4, v4
	ds_write_b16 v115, v4 offset:880
	s_waitcnt lgkmcnt(1)
	v_add_f32_e32 v5, v6, v22
	s_nop 1
	v_mov_b32_dpp v6, v5 row_mirror row_mask:0xf bank_mask:0xf
	v_mul_f32_e32 v4, v20, v38
	v_mul_f32_e32 v4, v19, v4
	s_nop 0
	v_cvt_pk_bf16_f32 v4, v4, v4
	ds_write_b16 v115, v4 offset:944
	s_waitcnt lgkmcnt(1)
	v_add_f32_e32 v5, v5, v6
	ds_bpermute_b32 v6, v3, v5
	v_mul_f32_e32 v4, v21, v38
	v_mul_f32_e32 v4, v18, v4
	s_nop 0
	v_cvt_pk_bf16_f32 v38, v4, v4
	v_mov_b32_e32 v54, v7
	s_waitcnt lgkmcnt(0)
	v_add_f32_e32 v4, v5, v6
	v_fmamk_f32 v52, v4, 0x3c000000, v187
	v_pk_mul_f32 v[4:5], v[54:55], v[142:143] op_sel_hi:[1,0]
	v_mov_b32_e32 v106, v111
	v_mov_b32_e32 v22, v39
	v_pk_fma_f32 v[4:5], v[188:189], v[4:5], v[106:107] neg_lo:[1,0,0] neg_hi:[1,0,0]
	v_pk_mul_f32 v[20:21], v[22:23], v[142:143] op_sel_hi:[1,0]
	v_mov_b32_e32 v98, v103
	v_pk_mul_f32 v[6:7], v[4:5], v[4:5]
	v_pk_fma_f32 v[20:21], v[188:189], v[20:21], v[98:99] neg_lo:[1,0,0] neg_hi:[1,0,0]
	v_add_f32_e32 v6, v6, v7
	v_pk_mul_f32 v[22:23], v[20:21], v[20:21]
	v_cmp_gt_f32_e32 vcc, s71, v52
	v_add_f32_e32 v6, v6, v22
	v_add_f32_e32 v6, v6, v23
	s_nop 1
	v_mov_b32_dpp v7, v6 quad_perm:[1,0,3,2] row_mask:0xf bank_mask:0xf
	v_mul_f32_e32 v22, 0x4b800000, v52
	v_cndmask_b32_e32 v22, v52, v22, vcc
	v_rsq_f32_e32 v22, v22
	ds_write_b16 v115, v38 offset:1008
	s_waitcnt lgkmcnt(1)
	v_add_f32_e32 v6, v6, v7
	s_nop 1
	v_mov_b32_dpp v7, v6 quad_perm:[2,3,0,1] row_mask:0xf bank_mask:0xf
	v_mul_f32_e32 v23, 0x45800000, v22
	v_cndmask_b32_e32 v22, v22, v23, vcc
	v_mul_f32_e32 v23, v36, v22
	v_mul_f32_e32 v23, v51, v23
	s_waitcnt lgkmcnt(0)
	v_add_f32_e32 v6, v6, v7
	s_nop 1
	v_mov_b32_dpp v7, v6 row_half_mirror row_mask:0xf bank_mask:0xf
	s_nop 0
	v_cvt_pk_bf16_f32 v23, v23, v23
	ds_write_b16 v115, v23 offset:2176
	v_mul_f32_e32 v23, v37, v22
	v_mul_f32_e32 v23, v50, v23
	s_waitcnt lgkmcnt(1)
	v_add_f32_e32 v6, v6, v7
	s_nop 1
	v_mov_b32_dpp v7, v6 row_mirror row_mask:0xf bank_mask:0xf
	s_nop 0
	v_cvt_pk_bf16_f32 v23, v23, v23
	ds_write_b16 v115, v23 offset:2240
	v_mul_f32_e32 v23, v116, v22
	v_mul_f32_e32 v23, v19, v23
	s_waitcnt lgkmcnt(1)
	v_add_f32_e32 v6, v6, v7
	ds_bpermute_b32 v7, v3, v6
	s_nop 0
	v_cvt_pk_bf16_f32 v23, v23, v23
	ds_write_b16 v115, v23 offset:2304
	v_mul_f32_e32 v52, v117, v22
	v_mov_b32_e32 v22, v112
	s_waitcnt lgkmcnt(1)
	v_add_f32_e32 v6, v6, v7
	v_fmamk_f32 v6, v6, 0x3c000000, v187
	v_mul_f32_e32 v7, 0x4b800000, v6
	v_cmp_gt_f32_e32 vcc, s71, v6
	v_mov_b32_e32 v23, v108
	v_mov_b32_e32 v36, v40
	v_cndmask_b32_e32 v6, v6, v7, vcc
	v_rsq_f32_e32 v53, v6
	v_mov_b32_e32 v6, v8
	v_mov_b32_e32 v7, v56
	v_pk_mul_f32 v[6:7], v[6:7], v[140:141] op_sel_hi:[1,0]
	v_mov_b32_e32 v37, v24
	v_pk_fma_f32 v[6:7], v[188:189], v[6:7], v[22:23] neg_lo:[1,0,0] neg_hi:[1,0,0]
	v_pk_mul_f32 v[36:37], v[36:37], v[140:141] op_sel_hi:[1,0]
	v_mov_b32_e32 v38, v104
	v_mov_b32_e32 v39, v100
	v_pk_mul_f32 v[22:23], v[6:7], v[6:7]
	v_pk_fma_f32 v[36:37], v[188:189], v[36:37], v[38:39] neg_lo:[1,0,0] neg_hi:[1,0,0]
	v_add_f32_e32 v8, v22, v23
	v_pk_mul_f32 v[38:39], v[36:37], v[36:37]
	v_mul_f32_e32 v23, v18, v52
	v_add_f32_e32 v8, v8, v38
	v_add_f32_e32 v8, v8, v39
	s_nop 1
	v_mov_b32_dpp v22, v8 quad_perm:[1,0,3,2] row_mask:0xf bank_mask:0xf
	s_nop 0
	v_cvt_pk_bf16_f32 v23, v23, v23
	ds_write_b16 v115, v23 offset:2368
	v_mul_f32_e32 v23, 0x45800000, v53
	v_cndmask_b32_e32 v23, v53, v23, vcc
	s_waitcnt lgkmcnt(1)
	v_add_f32_e32 v8, v8, v22
	s_nop 1
	v_mov_b32_dpp v22, v8 quad_perm:[2,3,0,1] row_mask:0xf bank_mask:0xf
	v_mul_f32_e32 v4, v4, v23
	v_mul_f32_e32 v4, v51, v4
	s_nop 0
	v_cvt_pk_bf16_f32 v4, v4, v4
	ds_write_b16 v115, v4 offset:2448
	s_waitcnt lgkmcnt(1)
	v_add_f32_e32 v8, v8, v22
	s_nop 1
	v_mov_b32_dpp v22, v8 row_half_mirror row_mask:0xf bank_mask:0xf
	v_mul_f32_e32 v4, v5, v23
	v_mul_f32_e32 v4, v50, v4
	s_nop 0
	v_cvt_pk_bf16_f32 v4, v4, v4
	ds_write_b16 v115, v4 offset:2512
	s_waitcnt lgkmcnt(1)
	v_add_f32_e32 v5, v8, v22
	s_nop 1
	v_mov_b32_dpp v8, v5 row_mirror row_mask:0xf bank_mask:0xf
	v_mul_f32_e32 v4, v20, v23
	v_mul_f32_e32 v4, v19, v4
	s_nop 0
	v_cvt_pk_bf16_f32 v4, v4, v4
	ds_write_b16 v115, v4 offset:2576
	s_waitcnt lgkmcnt(1)
	v_add_f32_e32 v5, v5, v8
	ds_bpermute_b32 v8, v3, v5
	v_mul_f32_e32 v4, v21, v23
	v_mul_f32_e32 v4, v18, v4
	s_nop 0
	v_cvt_pk_bf16_f32 v38, v4, v4
	v_mov_b32_e32 v56, v9
	s_waitcnt lgkmcnt(0)
	v_add_f32_e32 v4, v5, v8
	v_fmamk_f32 v39, v4, 0x3c000000, v187
	v_pk_mul_f32 v[4:5], v[56:57], v[138:139] op_sel_hi:[1,0]
	v_mov_b32_e32 v108, v113
	v_mov_b32_e32 v24, v41
	v_pk_fma_f32 v[4:5], v[188:189], v[4:5], v[108:109] neg_lo:[1,0,0] neg_hi:[1,0,0]
	v_pk_mul_f32 v[20:21], v[24:25], v[138:139] op_sel_hi:[1,0]
	v_mov_b32_e32 v100, v105
	v_pk_mul_f32 v[8:9], v[4:5], v[4:5]
	v_pk_fma_f32 v[20:21], v[188:189], v[20:21], v[100:101] neg_lo:[1,0,0] neg_hi:[1,0,0]
	v_add_f32_e32 v8, v8, v9
	v_pk_mul_f32 v[22:23], v[20:21], v[20:21]
	v_cmp_gt_f32_e32 vcc, s71, v39
	v_add_f32_e32 v8, v8, v22
	v_add_f32_e32 v8, v8, v23
	s_nop 1
	v_mov_b32_dpp v9, v8 quad_perm:[1,0,3,2] row_mask:0xf bank_mask:0xf
	v_mul_f32_e32 v22, 0x4b800000, v39
	v_cndmask_b32_e32 v22, v39, v22, vcc
	v_rsq_f32_e32 v22, v22
	ds_write_b16 v115, v38 offset:2640
	s_waitcnt lgkmcnt(1)
; __device__ __forceinline__ u16 f2bf(float f) { return (u16)(cvtpk(f, f) & 0xffffu); }
; __device__ __forceinline__ void phase3(const Params& p, char* shm) {
;     ...
;     { const f32x4* o1p = reinterpret_cast<const f32x4*>(o1s + tid * 64);
; #pragma unroll
;       for (int d0 = 0; d0 < 4; ++d0)
; #pragma unroll
;         for (int q = 0; q < 4; ++q) { const f32x4 v1 = o1p[d0 * 4 + q];
; #pragma unroll
;           for (int e = 0; e < 4; ++e) o[d0][q * 4 + e] = v1[e] - lam * o[d0][q * 4 + e]; } }
;     float sw[4];
; #pragma unroll
;     for (int d0 = 0; d0 < 4; ++d0) sw[d0] = p.subln[d0 * 32 + r32] * 0.8f;
;     char* const otb = shm + ((wid * 32 + 4 * hi) * OT_LD + r32) * 2;
; #pragma unroll
;     for (int r = 0; r < 16; ++r) {
;       float ss = 0.f;
; #pragma unroll
;       for (int d0 = 0; d0 < 4; ++d0) ss += o[d0][r] * o[d0][r];
;       ss += __shfl_xor(ss, 1); ss += __shfl_xor(ss, 2); ss += __shfl_xor(ss, 4); ss += __shfl_xor(ss, 8); ss += __shfl_xor(ss, 16);
;       const float rstd = rsqrtf(ss * (1.f / 128.f) + 1e-6f);
; #pragma unroll
;       for (int d0 = 0; d0 < 4; ++d0) *(u16*)(otb + (((r & 3) + 8 * (r >> 2)) * OT_LD + d0 * 32) * 2) = f2bf(o[d0][r] * rstd * sw[d0]);
;     }
	v_add_f32_e32 v8, v8, v9
	s_nop 1
	v_mov_b32_dpp v9, v8 quad_perm:[2,3,0,1] row_mask:0xf bank_mask:0xf
	v_mul_f32_e32 v23, 0x45800000, v22
	v_cndmask_b32_e32 v22, v22, v23, vcc
	v_mul_f32_e32 v6, v6, v22
	v_mul_f32_e32 v6, v51, v6
	s_waitcnt lgkmcnt(0)
	v_add_f32_e32 v8, v8, v9
	s_nop 1
	v_mov_b32_dpp v9, v8 row_half_mirror row_mask:0xf bank_mask:0xf
	s_nop 0
	v_cvt_pk_bf16_f32 v6, v6, v6
	ds_write_b16 v115, v6 offset:2720
	v_mul_f32_e32 v6, v7, v22
	v_mul_f32_e32 v6, v50, v6
	s_waitcnt lgkmcnt(1)
	v_add_f32_e32 v7, v8, v9
	s_nop 1
	v_mov_b32_dpp v8, v7 row_mirror row_mask:0xf bank_mask:0xf
	s_nop 0
	v_cvt_pk_bf16_f32 v6, v6, v6
	ds_write_b16 v115, v6 offset:2784
	v_mul_f32_e32 v6, v36, v22
	v_mul_f32_e32 v6, v19, v6
	s_waitcnt lgkmcnt(1)
	v_add_f32_e32 v7, v7, v8
	ds_bpermute_b32 v8, v3, v7
	s_nop 0
	v_cvt_pk_bf16_f32 v6, v6, v6
	ds_write_b16 v115, v6 offset:2848
	v_mul_f32_e32 v36, v37, v22
	s_waitcnt vmcnt(4)
	v_mov_b32_e32 v9, v94
	s_waitcnt lgkmcnt(1)
	v_add_f32_e32 v6, v7, v8
	v_fmamk_f32 v6, v6, 0x3c000000, v187
	v_mul_f32_e32 v7, 0x4b800000, v6
	v_cmp_gt_f32_e32 vcc, s71, v6
	v_mov_b32_e32 v8, v90
	v_mov_b32_e32 v22, v42
	v_cndmask_b32_e32 v6, v6, v7, vcc
	v_rsq_f32_e32 v37, v6
	v_mov_b32_e32 v6, v10
	v_mov_b32_e32 v7, v58
	v_pk_mul_f32 v[6:7], v[6:7], v[136:137] op_sel_hi:[1,0]
	v_mov_b32_e32 v23, v26
	v_pk_fma_f32 v[6:7], v[188:189], v[6:7], v[8:9] neg_lo:[1,0,0] neg_hi:[1,0,0]
	v_pk_mul_f32 v[22:23], v[22:23], v[136:137] op_sel_hi:[1,0]
	s_waitcnt vmcnt(2)
	v_mov_b32_e32 v24, v82
	s_waitcnt vmcnt(0)
	v_mov_b32_e32 v25, v86
	v_pk_mul_f32 v[8:9], v[6:7], v[6:7]
	v_pk_fma_f32 v[22:23], v[188:189], v[22:23], v[24:25] neg_lo:[1,0,0] neg_hi:[1,0,0]
	v_add_f32_e32 v8, v8, v9
	v_pk_mul_f32 v[24:25], v[22:23], v[22:23]
	v_mul_f32_e32 v10, v18, v36
	v_add_f32_e32 v8, v8, v24
	v_add_f32_e32 v8, v8, v25
	s_nop 1
	v_mov_b32_dpp v9, v8 quad_perm:[1,0,3,2] row_mask:0xf bank_mask:0xf
	s_nop 0
	v_cvt_pk_bf16_f32 v10, v10, v10
	ds_write_b16 v115, v10 offset:2912
	v_mul_f32_e32 v10, 0x45800000, v37
	v_cndmask_b32_e32 v10, v37, v10, vcc
	s_waitcnt lgkmcnt(1)
	v_add_f32_e32 v8, v8, v9
	s_nop 1
	v_mov_b32_dpp v9, v8 quad_perm:[2,3,0,1] row_mask:0xf bank_mask:0xf
	v_mul_f32_e32 v4, v4, v10
	v_mul_f32_e32 v4, v51, v4
	s_nop 0
	v_cvt_pk_bf16_f32 v4, v4, v4
	ds_write_b16 v115, v4 offset:2992
	s_waitcnt lgkmcnt(1)
	v_add_f32_e32 v8, v8, v9
	s_nop 1
	v_mov_b32_dpp v9, v8 row_half_mirror row_mask:0xf bank_mask:0xf
	v_mul_f32_e32 v4, v5, v10
	v_mul_f32_e32 v4, v50, v4
	s_nop 0
	v_cvt_pk_bf16_f32 v4, v4, v4
	ds_write_b16 v115, v4 offset:3056
	s_waitcnt lgkmcnt(1)
	v_add_f32_e32 v5, v8, v9
	s_nop 1
	v_mov_b32_dpp v8, v5 row_mirror row_mask:0xf bank_mask:0xf
	v_mul_f32_e32 v4, v20, v10
	v_mul_f32_e32 v4, v19, v4
	s_nop 0
	v_cvt_pk_bf16_f32 v4, v4, v4
	ds_write_b16 v115, v4 offset:3120
	s_waitcnt lgkmcnt(1)
	v_add_f32_e32 v5, v5, v8
	ds_bpermute_b32 v8, v3, v5
	v_mul_f32_e32 v4, v21, v10
	v_mul_f32_e32 v4, v18, v4
	s_nop 0
	v_cvt_pk_bf16_f32 v24, v4, v4
	v_mov_b32_e32 v58, v11
	s_waitcnt lgkmcnt(0)
	v_add_f32_e32 v4, v5, v8
	v_fmamk_f32 v25, v4, 0x3c000000, v187
	v_pk_mul_f32 v[4:5], v[58:59], v[134:135] op_sel_hi:[1,0]
	v_mov_b32_e32 v94, v91
	v_mov_b32_e32 v26, v43
	v_pk_fma_f32 v[4:5], v[188:189], v[4:5], v[94:95] neg_lo:[1,0,0] neg_hi:[1,0,0]
	v_pk_mul_f32 v[10:11], v[26:27], v[134:135] op_sel_hi:[1,0]
	v_mov_b32_e32 v86, v83
	v_pk_mul_f32 v[8:9], v[4:5], v[4:5]
	v_pk_fma_f32 v[10:11], v[188:189], v[10:11], v[86:87] neg_lo:[1,0,0] neg_hi:[1,0,0]
	v_add_f32_e32 v8, v8, v9
	v_pk_mul_f32 v[20:21], v[10:11], v[10:11]
	v_cmp_gt_f32_e32 vcc, s71, v25
	v_add_f32_e32 v8, v8, v20
	v_add_f32_e32 v8, v8, v21
	s_nop 1
	v_mov_b32_dpp v9, v8 quad_perm:[1,0,3,2] row_mask:0xf bank_mask:0xf
	v_mul_f32_e32 v20, 0x4b800000, v25
	v_cndmask_b32_e32 v20, v25, v20, vcc
	v_rsq_f32_e32 v20, v20
	ds_write_b16 v115, v24 offset:3184
	s_waitcnt lgkmcnt(1)
	v_add_f32_e32 v8, v8, v9
	s_nop 1
	v_mov_b32_dpp v9, v8 quad_perm:[2,3,0,1] row_mask:0xf bank_mask:0xf
	v_mul_f32_e32 v21, 0x45800000, v20
	v_cndmask_b32_e32 v20, v20, v21, vcc
	v_mul_f32_e32 v6, v6, v20
	v_mul_f32_e32 v6, v51, v6
	s_waitcnt lgkmcnt(0)
	v_add_f32_e32 v8, v8, v9
	s_nop 1
	v_mov_b32_dpp v9, v8 row_half_mirror row_mask:0xf bank_mask:0xf
	s_nop 0
	v_cvt_pk_bf16_f32 v6, v6, v6
	ds_write_b16 v115, v6 offset:4352
	v_mul_f32_e32 v6, v7, v20
	v_mul_f32_e32 v6, v50, v6
	s_waitcnt lgkmcnt(1)
	v_add_f32_e32 v7, v8, v9
	s_nop 1
	v_mov_b32_dpp v8, v7 row_mirror row_mask:0xf bank_mask:0xf
	s_nop 0
	v_cvt_pk_bf16_f32 v6, v6, v6
	ds_write_b16 v115, v6 offset:4416
	v_mul_f32_e32 v6, v22, v20
	v_mul_f32_e32 v6, v19, v6
	s_waitcnt lgkmcnt(1)
	v_add_f32_e32 v7, v7, v8
	ds_bpermute_b32 v8, v3, v7
	s_nop 0
	v_cvt_pk_bf16_f32 v6, v6, v6
	ds_write_b16 v115, v6 offset:4480
	v_mul_f32_e32 v24, v23, v20
	v_mov_b32_e32 v9, v96
	s_waitcnt lgkmcnt(1)
	v_add_f32_e32 v6, v7, v8
	v_fmamk_f32 v6, v6, 0x3c000000, v187
	v_mul_f32_e32 v7, 0x4b800000, v6
	v_cmp_gt_f32_e32 vcc, s71, v6
	v_mov_b32_e32 v8, v92
	v_mov_b32_e32 v20, v44
	v_cndmask_b32_e32 v6, v6, v7, vcc
	v_rsq_f32_e32 v25, v6
	v_mov_b32_e32 v6, v12
	v_mov_b32_e32 v7, v60
	v_pk_mul_f32 v[6:7], v[6:7], v[132:133] op_sel_hi:[1,0]
	v_mov_b32_e32 v21, v28
	v_pk_fma_f32 v[6:7], v[188:189], v[6:7], v[8:9] neg_lo:[1,0,0] neg_hi:[1,0,0]
	v_pk_mul_f32 v[20:21], v[20:21], v[132:133] op_sel_hi:[1,0]
	v_mov_b32_e32 v22, v84
	v_mov_b32_e32 v23, v88
	v_pk_mul_f32 v[8:9], v[6:7], v[6:7]
	v_pk_fma_f32 v[20:21], v[188:189], v[20:21], v[22:23] neg_lo:[1,0,0] neg_hi:[1,0,0]
	v_add_f32_e32 v8, v8, v9
	v_pk_mul_f32 v[22:23], v[20:21], v[20:21]
	v_mul_f32_e32 v12, v18, v24
	v_add_f32_e32 v8, v8, v22
	v_add_f32_e32 v8, v8, v23
	s_nop 1
	v_mov_b32_dpp v9, v8 quad_perm:[1,0,3,2] row_mask:0xf bank_mask:0xf
	s_nop 0
	v_cvt_pk_bf16_f32 v12, v12, v12
	ds_write_b16 v115, v12 offset:4544
	v_mul_f32_e32 v12, 0x45800000, v25
	v_cndmask_b32_e32 v12, v25, v12, vcc
	s_waitcnt lgkmcnt(1)
; __device__ __forceinline__ u16 f2bf(float f) { return (u16)(cvtpk(f, f) & 0xffffu); }
; __device__ __forceinline__ void phase3(const Params& p, char* shm) {
;     ...
;     { const f32x4* o1p = reinterpret_cast<const f32x4*>(o1s + tid * 64);
; #pragma unroll
;       for (int d0 = 0; d0 < 4; ++d0)
; #pragma unroll
;         for (int q = 0; q < 4; ++q) { const f32x4 v1 = o1p[d0 * 4 + q];
; #pragma unroll
;           for (int e = 0; e < 4; ++e) o[d0][q * 4 + e] = v1[e] - lam * o[d0][q * 4 + e]; } }
;     float sw[4];
; #pragma unroll
;     for (int d0 = 0; d0 < 4; ++d0) sw[d0] = p.subln[d0 * 32 + r32] * 0.8f;
;     char* const otb = shm + ((wid * 32 + 4 * hi) * OT_LD + r32) * 2;
; #pragma unroll
;     for (int r = 0; r < 16; ++r) {
;       float ss = 0.f;
; #pragma unroll
;       for (int d0 = 0; d0 < 4; ++d0) ss += o[d0][r] * o[d0][r];
;       ss += __shfl_xor(ss, 1); ss += __shfl_xor(ss, 2); ss += __shfl_xor(ss, 4); ss += __shfl_xor(ss, 8); ss += __shfl_xor(ss, 16);
;       const float rstd = rsqrtf(ss * (1.f / 128.f) + 1e-6f);
; #pragma unroll
;       for (int d0 = 0; d0 < 4; ++d0) *(u16*)(otb + (((r & 3) + 8 * (r >> 2)) * OT_LD + d0 * 32) * 2) = f2bf(o[d0][r] * rstd * sw[d0]);
;     }
	v_add_f32_e32 v8, v8, v9
	s_nop 1
	v_mov_b32_dpp v9, v8 quad_perm:[2,3,0,1] row_mask:0xf bank_mask:0xf
	v_mul_f32_e32 v4, v4, v12
	v_mul_f32_e32 v4, v51, v4
	s_nop 0
	v_cvt_pk_bf16_f32 v4, v4, v4
	ds_write_b16 v115, v4 offset:4624
	s_waitcnt lgkmcnt(1)
	v_add_f32_e32 v8, v8, v9
	s_nop 1
	v_mov_b32_dpp v9, v8 row_half_mirror row_mask:0xf bank_mask:0xf
	v_mul_f32_e32 v4, v5, v12
	v_mul_f32_e32 v4, v50, v4
	s_nop 0
	v_cvt_pk_bf16_f32 v4, v4, v4
	ds_write_b16 v115, v4 offset:4688
	s_waitcnt lgkmcnt(1)
	v_add_f32_e32 v5, v8, v9
	s_nop 1
	v_mov_b32_dpp v8, v5 row_mirror row_mask:0xf bank_mask:0xf
	v_mul_f32_e32 v4, v10, v12
	v_mul_f32_e32 v4, v19, v4
	s_nop 0
	v_cvt_pk_bf16_f32 v4, v4, v4
	ds_write_b16 v115, v4 offset:4752
	s_waitcnt lgkmcnt(1)
	v_add_f32_e32 v5, v5, v8
	ds_bpermute_b32 v8, v3, v5
	v_mul_f32_e32 v4, v11, v12
	v_mul_f32_e32 v4, v18, v4
	s_nop 0
	v_cvt_pk_bf16_f32 v22, v4, v4
	v_mov_b32_e32 v60, v13
	s_waitcnt lgkmcnt(0)
	v_add_f32_e32 v4, v5, v8
	v_fmamk_f32 v23, v4, 0x3c000000, v187
	v_pk_mul_f32 v[4:5], v[60:61], v[130:131] op_sel_hi:[1,0]
	v_mov_b32_e32 v96, v93
	v_mov_b32_e32 v28, v45
	v_pk_fma_f32 v[4:5], v[188:189], v[4:5], v[96:97] neg_lo:[1,0,0] neg_hi:[1,0,0]
	v_pk_mul_f32 v[10:11], v[28:29], v[130:131] op_sel_hi:[1,0]
	v_mov_b32_e32 v88, v85
	v_pk_mul_f32 v[8:9], v[4:5], v[4:5]
	v_pk_fma_f32 v[10:11], v[188:189], v[10:11], v[88:89] neg_lo:[1,0,0] neg_hi:[1,0,0]
	v_add_f32_e32 v8, v8, v9
	v_pk_mul_f32 v[12:13], v[10:11], v[10:11]
	v_cmp_gt_f32_e32 vcc, s71, v23
	v_add_f32_e32 v8, v8, v12
	v_add_f32_e32 v8, v8, v13
	s_nop 1
	v_mov_b32_dpp v9, v8 quad_perm:[1,0,3,2] row_mask:0xf bank_mask:0xf
	v_mul_f32_e32 v12, 0x4b800000, v23
	v_cndmask_b32_e32 v12, v23, v12, vcc
	v_rsq_f32_e32 v12, v12
	ds_write_b16 v115, v22 offset:4816
	s_waitcnt lgkmcnt(1)
	v_add_f32_e32 v8, v8, v9
	s_nop 1
	v_mov_b32_dpp v9, v8 quad_perm:[2,3,0,1] row_mask:0xf bank_mask:0xf
	v_mul_f32_e32 v13, 0x45800000, v12
	v_cndmask_b32_e32 v12, v12, v13, vcc
	v_mul_f32_e32 v6, v6, v12
	v_mul_f32_e32 v6, v51, v6
	s_waitcnt lgkmcnt(0)
	v_add_f32_e32 v8, v8, v9
	s_nop 1
	v_mov_b32_dpp v9, v8 row_half_mirror row_mask:0xf bank_mask:0xf
	s_nop 0
	v_cvt_pk_bf16_f32 v6, v6, v6
	ds_write_b16 v115, v6 offset:4896
	v_mul_f32_e32 v6, v7, v12
	v_mul_f32_e32 v6, v50, v6
	s_waitcnt lgkmcnt(1)
	v_add_f32_e32 v7, v8, v9
	s_nop 1
	v_mov_b32_dpp v8, v7 row_mirror row_mask:0xf bank_mask:0xf
	s_nop 0
	v_cvt_pk_bf16_f32 v6, v6, v6
	ds_write_b16 v115, v6 offset:4960
	v_mul_f32_e32 v6, v20, v12
	v_mul_f32_e32 v6, v19, v6
	s_waitcnt lgkmcnt(1)
	v_add_f32_e32 v7, v7, v8
	ds_bpermute_b32 v8, v3, v7
	s_nop 0
	v_cvt_pk_bf16_f32 v6, v6, v6
	ds_write_b16 v115, v6 offset:5024
	v_mul_f32_e32 v22, v21, v12
	v_mov_b32_e32 v9, v78
	s_waitcnt lgkmcnt(1)
	v_add_f32_e32 v6, v7, v8
	v_fmamk_f32 v6, v6, 0x3c000000, v187
	v_mul_f32_e32 v7, 0x4b800000, v6
	v_cmp_gt_f32_e32 vcc, s71, v6
	v_mov_b32_e32 v8, v74
	v_mov_b32_e32 v12, v46
	v_cndmask_b32_e32 v6, v6, v7, vcc
	v_rsq_f32_e32 v23, v6
	v_mov_b32_e32 v6, v14
	v_mov_b32_e32 v7, v62
	v_pk_mul_f32 v[6:7], v[6:7], v[118:119] op_sel_hi:[1,0]
	v_mov_b32_e32 v13, v30
	v_pk_fma_f32 v[6:7], v[188:189], v[6:7], v[8:9] neg_lo:[1,0,0] neg_hi:[1,0,0]
	v_pk_mul_f32 v[12:13], v[12:13], v[118:119] op_sel_hi:[1,0]
	v_mov_b32_e32 v20, v66
	v_mov_b32_e32 v21, v70
	v_pk_mul_f32 v[8:9], v[6:7], v[6:7]
	v_pk_fma_f32 v[12:13], v[188:189], v[12:13], v[20:21] neg_lo:[1,0,0] neg_hi:[1,0,0]
	v_add_f32_e32 v8, v8, v9
	v_pk_mul_f32 v[20:21], v[12:13], v[12:13]
	v_mul_f32_e32 v14, v18, v22
	v_add_f32_e32 v8, v8, v20
	v_add_f32_e32 v8, v8, v21
	s_nop 1
	v_mov_b32_dpp v9, v8 quad_perm:[1,0,3,2] row_mask:0xf bank_mask:0xf
	s_nop 0
	v_cvt_pk_bf16_f32 v14, v14, v14
	ds_write_b16 v115, v14 offset:5088
	v_mul_f32_e32 v14, 0x45800000, v23
	v_cndmask_b32_e32 v14, v23, v14, vcc
	s_waitcnt lgkmcnt(1)
	v_add_f32_e32 v8, v8, v9
	s_nop 1
	v_mov_b32_dpp v9, v8 quad_perm:[2,3,0,1] row_mask:0xf bank_mask:0xf
	v_mul_f32_e32 v4, v4, v14
	v_mul_f32_e32 v4, v51, v4
	s_nop 0
	v_cvt_pk_bf16_f32 v4, v4, v4
	ds_write_b16 v115, v4 offset:5168
	s_waitcnt lgkmcnt(1)
	v_add_f32_e32 v8, v8, v9
	s_nop 1
	v_mov_b32_dpp v9, v8 row_half_mirror row_mask:0xf bank_mask:0xf
	v_mul_f32_e32 v4, v5, v14
	v_mul_f32_e32 v4, v50, v4
	s_nop 0
	v_cvt_pk_bf16_f32 v4, v4, v4
	ds_write_b16 v115, v4 offset:5232
	s_waitcnt lgkmcnt(1)
	v_add_f32_e32 v5, v8, v9
	s_nop 1
	v_mov_b32_dpp v8, v5 row_mirror row_mask:0xf bank_mask:0xf
	v_mul_f32_e32 v4, v10, v14
	v_mul_f32_e32 v4, v19, v4
	s_nop 0
	v_cvt_pk_bf16_f32 v4, v4, v4
	ds_write_b16 v115, v4 offset:5296
	s_waitcnt lgkmcnt(1)
	v_add_f32_e32 v5, v5, v8
	ds_bpermute_b32 v8, v3, v5
	v_mul_f32_e32 v4, v11, v14
	v_mul_f32_e32 v4, v18, v4
	s_nop 0
	v_cvt_pk_bf16_f32 v20, v4, v4
	v_mov_b32_e32 v62, v15
	s_waitcnt lgkmcnt(0)
	v_add_f32_e32 v4, v5, v8
	v_fmamk_f32 v21, v4, 0x3c000000, v187
	v_pk_mul_f32 v[4:5], v[62:63], v[114:115] op_sel_hi:[1,0]
	v_mov_b32_e32 v78, v75
	v_mov_b32_e32 v30, v47
	v_pk_fma_f32 v[4:5], v[188:189], v[4:5], v[78:79] neg_lo:[1,0,0] neg_hi:[1,0,0]
	v_pk_mul_f32 v[10:11], v[30:31], v[114:115] op_sel_hi:[1,0]
	v_mov_b32_e32 v70, v67
	v_pk_mul_f32 v[8:9], v[4:5], v[4:5]
	v_pk_fma_f32 v[10:11], v[188:189], v[10:11], v[70:71] neg_lo:[1,0,0] neg_hi:[1,0,0]
	v_add_f32_e32 v8, v8, v9
	v_pk_mul_f32 v[14:15], v[10:11], v[10:11]
	v_cmp_gt_f32_e32 vcc, s71, v21
	v_add_f32_e32 v8, v8, v14
	v_add_f32_e32 v8, v8, v15
	s_nop 1
	v_mov_b32_dpp v9, v8 quad_perm:[1,0,3,2] row_mask:0xf bank_mask:0xf
	v_mul_f32_e32 v14, 0x4b800000, v21
	v_cndmask_b32_e32 v14, v21, v14, vcc
	v_rsq_f32_e32 v14, v14
	ds_write_b16 v115, v20 offset:5360
	s_waitcnt lgkmcnt(1)
; __device__ __forceinline__ u16 f2bf(float f) { return (u16)(cvtpk(f, f) & 0xffffu); }
; __device__ __forceinline__ void phase3(const Params& p, char* shm) {
;     ...
;     { const f32x4* o1p = reinterpret_cast<const f32x4*>(o1s + tid * 64);
; #pragma unroll
;       for (int d0 = 0; d0 < 4; ++d0)
; #pragma unroll
;         for (int q = 0; q < 4; ++q) { const f32x4 v1 = o1p[d0 * 4 + q];
; #pragma unroll
;           for (int e = 0; e < 4; ++e) o[d0][q * 4 + e] = v1[e] - lam * o[d0][q * 4 + e]; } }
;     float sw[4];
; #pragma unroll
;     for (int d0 = 0; d0 < 4; ++d0) sw[d0] = p.subln[d0 * 32 + r32] * 0.8f;
;     char* const otb = shm + ((wid * 32 + 4 * hi) * OT_LD + r32) * 2;
; #pragma unroll
;     for (int r = 0; r < 16; ++r) {
;       float ss = 0.f;
; #pragma unroll
;       for (int d0 = 0; d0 < 4; ++d0) ss += o[d0][r] * o[d0][r];
;       ss += __shfl_xor(ss, 1); ss += __shfl_xor(ss, 2); ss += __shfl_xor(ss, 4); ss += __shfl_xor(ss, 8); ss += __shfl_xor(ss, 16);
;       const float rstd = rsqrtf(ss * (1.f / 128.f) + 1e-6f);
; #pragma unroll
;       for (int d0 = 0; d0 < 4; ++d0) *(u16*)(otb + (((r & 3) + 8 * (r >> 2)) * OT_LD + d0 * 32) * 2) = f2bf(o[d0][r] * rstd * sw[d0]);
;     }
;     __syncthreads();
;     { const u16* zsrc = Zb + t0 * AW + h * 128; u16* bdst = Bin + t0 * AW + h * 128;
; #pragma unroll 2
;       for (int id = tid; id < 256 * 16; id += NTHR) {
	v_add_f32_e32 v8, v8, v9
	s_nop 1
	v_mov_b32_dpp v9, v8 quad_perm:[2,3,0,1] row_mask:0xf bank_mask:0xf
	v_mul_f32_e32 v15, 0x45800000, v14
	v_cndmask_b32_e32 v14, v14, v15, vcc
	v_mul_f32_e32 v6, v6, v14
	v_mul_f32_e32 v6, v51, v6
	s_waitcnt lgkmcnt(0)
	v_add_f32_e32 v8, v8, v9
	s_nop 1
	v_mov_b32_dpp v9, v8 row_half_mirror row_mask:0xf bank_mask:0xf
	s_nop 0
	v_cvt_pk_bf16_f32 v6, v6, v6
	ds_write_b16 v115, v6 offset:6528
	v_mul_f32_e32 v6, v7, v14
	v_mul_f32_e32 v6, v50, v6
	s_waitcnt lgkmcnt(1)
	v_add_f32_e32 v7, v8, v9
	s_nop 1
	v_mov_b32_dpp v8, v7 row_mirror row_mask:0xf bank_mask:0xf
	s_nop 0
	v_cvt_pk_bf16_f32 v6, v6, v6
	ds_write_b16 v115, v6 offset:6592
	v_mul_f32_e32 v6, v12, v14
	v_mul_f32_e32 v6, v19, v6
	s_waitcnt lgkmcnt(1)
	v_add_f32_e32 v7, v7, v8
	ds_bpermute_b32 v8, v3, v7
	s_nop 0
	v_cvt_pk_bf16_f32 v6, v6, v6
	ds_write_b16 v115, v6 offset:6656
	v_mul_f32_e32 v20, v13, v14
	v_mov_b32_e32 v9, v80
	s_waitcnt lgkmcnt(1)
	v_add_f32_e32 v6, v7, v8
	v_fmamk_f32 v6, v6, 0x3c000000, v187
	v_mul_f32_e32 v7, 0x4b800000, v6
	v_cmp_gt_f32_e32 vcc, s71, v6
	v_mov_b32_e32 v8, v76
	v_mov_b32_e32 v12, v48
	v_cndmask_b32_e32 v6, v6, v7, vcc
	v_rsq_f32_e32 v21, v6
	v_mov_b32_e32 v6, v16
	v_mov_b32_e32 v7, v64
	v_pk_mul_f32 v[6:7], v[6:7], v[34:35] op_sel_hi:[1,0]
	v_mov_b32_e32 v13, v32
	v_pk_fma_f32 v[6:7], v[188:189], v[6:7], v[8:9] neg_lo:[1,0,0] neg_hi:[1,0,0]
	v_pk_mul_f32 v[12:13], v[12:13], v[34:35] op_sel_hi:[1,0]
	v_mov_b32_e32 v14, v68
	v_mov_b32_e32 v15, v72
	v_pk_mul_f32 v[8:9], v[6:7], v[6:7]
	v_pk_fma_f32 v[12:13], v[188:189], v[12:13], v[14:15] neg_lo:[1,0,0] neg_hi:[1,0,0]
	v_add_f32_e32 v8, v8, v9
	v_pk_mul_f32 v[14:15], v[12:13], v[12:13]
	v_mov_b32_e32 v64, v17
	v_add_f32_e32 v8, v8, v14
	v_add_f32_e32 v8, v8, v15
	s_nop 1
	v_mov_b32_dpp v9, v8 quad_perm:[1,0,3,2] row_mask:0xf bank_mask:0xf
	v_mul_f32_e32 v14, v18, v20
	s_nop 0
	v_cvt_pk_bf16_f32 v14, v14, v14
	ds_write_b16 v115, v14 offset:6720
	v_mul_f32_e32 v14, 0x45800000, v21
	s_waitcnt lgkmcnt(1)
	v_add_f32_e32 v8, v8, v9
	s_nop 1
	v_mov_b32_dpp v9, v8 quad_perm:[2,3,0,1] row_mask:0xf bank_mask:0xf
	v_cndmask_b32_e32 v14, v21, v14, vcc
	v_mul_f32_e32 v4, v4, v14
	v_mul_f32_e32 v4, v51, v4
	s_nop 0
	v_cvt_pk_bf16_f32 v4, v4, v4
	s_waitcnt lgkmcnt(0)
	v_add_f32_e32 v8, v8, v9
	s_nop 1
	v_mov_b32_dpp v9, v8 row_half_mirror row_mask:0xf bank_mask:0xf
	ds_write_b16 v115, v4 offset:6800
	v_mul_f32_e32 v4, v5, v14
	v_mul_f32_e32 v4, v50, v4
	s_nop 0
	v_cvt_pk_bf16_f32 v4, v4, v4
	s_waitcnt lgkmcnt(1)
	v_add_f32_e32 v5, v8, v9
	s_nop 1
	v_mov_b32_dpp v8, v5 row_mirror row_mask:0xf bank_mask:0xf
	ds_write_b16 v115, v4 offset:6864
	v_mul_f32_e32 v4, v10, v14
	v_mul_f32_e32 v4, v19, v4
	s_nop 0
	v_cvt_pk_bf16_f32 v4, v4, v4
	s_waitcnt lgkmcnt(1)
	v_add_f32_e32 v5, v5, v8
	ds_bpermute_b32 v8, v3, v5
	ds_write_b16 v115, v4 offset:6928
	v_mul_f32_e32 v4, v11, v14
	v_mul_f32_e32 v4, v18, v4
	s_nop 0
	v_cvt_pk_bf16_f32 v16, v4, v4
	s_waitcnt lgkmcnt(1)
	v_add_f32_e32 v4, v5, v8
	v_fmamk_f32 v20, v4, 0x3c000000, v187
	v_pk_mul_f32 v[4:5], v[64:65], v[2:3] op_sel_hi:[1,0]
	v_mov_b32_e32 v80, v77
	v_mov_b32_e32 v32, v49
	v_pk_fma_f32 v[4:5], v[188:189], v[4:5], v[80:81] neg_lo:[1,0,0] neg_hi:[1,0,0]
	v_pk_mul_f32 v[10:11], v[32:33], v[2:3] op_sel_hi:[1,0]
	v_mov_b32_e32 v72, v69
	v_pk_mul_f32 v[8:9], v[4:5], v[4:5]
	v_pk_fma_f32 v[10:11], v[188:189], v[10:11], v[72:73] neg_lo:[1,0,0] neg_hi:[1,0,0]
	v_add_f32_e32 v2, v8, v9
	v_pk_mul_f32 v[14:15], v[10:11], v[10:11]
	v_mul_f32_e32 v9, 0x4b800000, v20
	v_add_f32_e32 v2, v2, v14
	v_add_f32_e32 v2, v2, v15
	s_nop 1
	v_mov_b32_dpp v8, v2 quad_perm:[1,0,3,2] row_mask:0xf bank_mask:0xf
	v_cmp_gt_f32_e32 vcc, s71, v20
	ds_write_b16 v115, v16 offset:6992
	s_waitcnt lgkmcnt(1)
	v_add_f32_e32 v2, v2, v8
	s_nop 1
	v_mov_b32_dpp v8, v2 quad_perm:[2,3,0,1] row_mask:0xf bank_mask:0xf
	v_cndmask_b32_e32 v9, v20, v9, vcc
	v_rsq_f32_e32 v9, v9
	s_waitcnt lgkmcnt(0)
	v_add_f32_e32 v2, v2, v8
	s_nop 1
	v_mov_b32_dpp v8, v2 row_half_mirror row_mask:0xf bank_mask:0xf
	v_mul_f32_e32 v14, 0x45800000, v9
	v_cndmask_b32_e32 v9, v9, v14, vcc
	v_mul_f32_e32 v6, v6, v9
	v_mul_f32_e32 v6, v51, v6
	s_nop 0
	v_cvt_pk_bf16_f32 v6, v6, v6
	s_waitcnt lgkmcnt(0)
	v_add_f32_e32 v2, v2, v8
	ds_write_b16 v115, v6 offset:7072
	v_mul_f32_e32 v6, v7, v9
	s_nop 1
	v_mov_b32_dpp v7, v2 row_mirror row_mask:0xf bank_mask:0xf
	v_mul_f32_e32 v6, v50, v6
	s_nop 0
	v_cvt_pk_bf16_f32 v6, v6, v6
	ds_write_b16 v115, v6 offset:7136
	v_mul_f32_e32 v6, v12, v9
	s_waitcnt lgkmcnt(1)
	v_add_f32_e32 v2, v2, v7
	ds_bpermute_b32 v3, v3, v2
	v_mul_f32_e32 v6, v19, v6
	s_nop 0
	v_cvt_pk_bf16_f32 v6, v6, v6
	ds_write_b16 v115, v6 offset:7200
	v_mul_f32_e32 v6, v13, v9
	s_waitcnt lgkmcnt(1)
	v_add_f32_e32 v2, v2, v3
	v_fmamk_f32 v2, v2, 0x3c000000, v187
	v_mul_f32_e32 v3, 0x4b800000, v2
	v_cmp_gt_f32_e32 vcc, s71, v2
	s_nop 1
	v_cndmask_b32_e32 v2, v2, v3, vcc
	v_rsq_f32_e32 v2, v2
	v_mul_f32_e32 v3, v18, v6
	s_nop 0
	v_cvt_pk_bf16_f32 v3, v3, v3
	ds_write_b16 v115, v3 offset:7264
	v_mul_f32_e32 v3, 0x45800000, v2
	v_cndmask_b32_e32 v2, v2, v3, vcc
	v_mul_f32_e32 v3, v4, v2
	v_mul_f32_e32 v3, v51, v3
	s_nop 0
	v_cvt_pk_bf16_f32 v3, v3, v3
	ds_write_b16 v115, v3 offset:7344
	v_mul_f32_e32 v3, v5, v2
	v_mul_f32_e32 v3, v50, v3
	s_nop 0
	v_cvt_pk_bf16_f32 v3, v3, v3
	ds_write_b16 v115, v3 offset:7408
	v_mul_f32_e32 v3, v10, v2
	v_mul_f32_e32 v2, v11, v2
	v_mul_f32_e32 v3, v19, v3
	v_mul_f32_e32 v2, v18, v2
	v_cmp_gt_i32_e32 vcc, s72, v131
	s_nop 0
	v_cvt_pk_bf16_f32 v3, v3, v3
	ds_write_b16 v115, v3 offset:7472
	s_nop 0
	v_cvt_pk_bf16_f32 v2, v2, v2
	ds_write_b16 v115, v2 offset:7536
	s_waitcnt lgkmcnt(0)
	s_barrier
; __device__ __forceinline__ float bflo(unsigned v) { return __uint_as_float(v << 16); }
; __device__ __forceinline__ float bfhi(unsigned v) { return __uint_as_float(v & 0xffff0000u); }
; __device__ __forceinline__ void phase3(const Params& p, char* shm) {
;     ...
;     { const u16* zsrc = Zb + t0 * AW + h * 128; u16* bdst = Bin + t0 * AW + h * 128;
; #pragma unroll 2
;       for (int id = tid; id < 256 * 16; id += NTHR) {
;         const int row = id >> 4, c = id & 15;
;         const u32x4 ov = *reinterpret_cast<const u32x4*>(shm + (row * OT_LD + c * 8) * 2);
;         const u32x4 zv = *reinterpret_cast<const u32x4*>(zsrc + (size_t)row * AW + c * 8);
;         u32x4 w;
; #pragma unroll
;         for (int q = 0; q < 4; ++q) w[q] = cvtpk(bflo(ov[q]) * bflo(zv[q]), bfhi(ov[q]) * bfhi(zv[q]));
;         *reinterpret_cast<u32x4*>(bdst + (size_t)row * AW + c * 8) = w;
;       }
	s_and_saveexec_b64 s[0:1], vcc
	s_cbranch_execz .LBB0_322
	s_add_u32 s4, s79, s18
	s_addc_u32 s5, s80, s19
	s_add_u32 s4, s4, s86
	s_addc_u32 s5, s5, 0
	s_add_u32 s6, s81, s18
	s_addc_u32 s7, s82, s19
	s_add_u32 s6, s6, s86
	s_addc_u32 s7, s7, 0
	v_lshlrev_b32_e32 v2, 3, v131
	v_lshrrev_b32_e32 v52, 4, v131
	v_and_b32_e32 v53, 15, v131
	v_lshlrev_b32_e32 v54, 11, v52
	v_lshl_add_u32 v54, v53, 4, v54
	v_mul_u32_u24_e32 v52, 0x110, v52
	v_lshl_add_u32 v52, v53, 4, v52
	v_add_u32_e32 v55, 0x10000, v54
	v_add_u32_e32 v56, 0x20000, v54
	v_add_u32_e32 v57, 0x30000, v54
	v_add_u32_e32 v58, 0x40000, v54
	v_add_u32_e32 v59, 0x50000, v54
	v_add_u32_e32 v60, 0x60000, v54
	v_add_u32_e32 v61, 0x70000, v54
	global_load_dwordx4 v[4:7], v54, s[4:5]
	global_load_dwordx4 v[8:11], v55, s[4:5]
	global_load_dwordx4 v[12:15], v56, s[4:5]
	global_load_dwordx4 v[16:19], v57, s[4:5]
	global_load_dwordx4 v[20:23], v58, s[4:5]
	global_load_dwordx4 v[24:27], v59, s[4:5]
	global_load_dwordx4 v[28:31], v60, s[4:5]
	global_load_dwordx4 v[32:35], v61, s[4:5]
	ds_read_b128 v[36:39], v52
	ds_read_b128 v[40:43], v52 offset:8704
	ds_read_b128 v[44:47], v52 offset:17408
	ds_read_b128 v[48:51], v52 offset:26112
	s_waitcnt vmcnt(7) lgkmcnt(3)
	v_lshlrev_b32_e32 v62, 16, v36
	v_lshlrev_b32_e32 v63, 16, v4
	v_and_b32_e32 v36, 0xffff0000, v36
	v_and_b32_e32 v4, 0xffff0000, v4
	v_mul_f32_e32 v62, v63, v62
	v_mul_f32_e32 v4, v4, v36
	v_cvt_pk_bf16_f32 v4, v62, v4
	v_lshlrev_b32_e32 v62, 16, v37
	v_lshlrev_b32_e32 v63, 16, v5
	v_and_b32_e32 v37, 0xffff0000, v37
	v_and_b32_e32 v5, 0xffff0000, v5
	v_mul_f32_e32 v62, v63, v62
	v_mul_f32_e32 v5, v5, v37
	v_cvt_pk_bf16_f32 v5, v62, v5
	v_lshlrev_b32_e32 v62, 16, v38
	v_lshlrev_b32_e32 v63, 16, v6
	v_and_b32_e32 v38, 0xffff0000, v38
	v_and_b32_e32 v6, 0xffff0000, v6
	v_mul_f32_e32 v62, v63, v62
	v_mul_f32_e32 v6, v6, v38
	v_cvt_pk_bf16_f32 v6, v62, v6
	v_lshlrev_b32_e32 v62, 16, v39
	v_lshlrev_b32_e32 v63, 16, v7
	v_and_b32_e32 v39, 0xffff0000, v39
	v_and_b32_e32 v7, 0xffff0000, v7
	v_mul_f32_e32 v62, v63, v62
	v_mul_f32_e32 v7, v7, v39
	v_cvt_pk_bf16_f32 v7, v62, v7
	global_store_dwordx4 v54, v[4:7], s[6:7]
	s_waitcnt vmcnt(7) lgkmcnt(2)
	v_lshlrev_b32_e32 v62, 16, v40
	v_lshlrev_b32_e32 v63, 16, v8
	v_and_b32_e32 v40, 0xffff0000, v40
	v_and_b32_e32 v8, 0xffff0000, v8
	v_mul_f32_e32 v62, v63, v62
	v_mul_f32_e32 v8, v8, v40
	v_cvt_pk_bf16_f32 v8, v62, v8
	v_lshlrev_b32_e32 v62, 16, v41
	v_lshlrev_b32_e32 v63, 16, v9
	v_and_b32_e32 v41, 0xffff0000, v41
	v_and_b32_e32 v9, 0xffff0000, v9
	v_mul_f32_e32 v62, v63, v62
	v_mul_f32_e32 v9, v9, v41
	v_cvt_pk_bf16_f32 v9, v62, v9
	v_lshlrev_b32_e32 v62, 16, v42
	v_lshlrev_b32_e32 v63, 16, v10
	v_and_b32_e32 v42, 0xffff0000, v42
	v_and_b32_e32 v10, 0xffff0000, v10
	v_mul_f32_e32 v62, v63, v62
	v_mul_f32_e32 v10, v10, v42
	v_cvt_pk_bf16_f32 v10, v62, v10
	v_lshlrev_b32_e32 v62, 16, v43
	v_lshlrev_b32_e32 v63, 16, v11
	v_and_b32_e32 v43, 0xffff0000, v43
	v_and_b32_e32 v11, 0xffff0000, v11
	v_mul_f32_e32 v62, v63, v62
	v_mul_f32_e32 v11, v11, v43
	v_cvt_pk_bf16_f32 v11, v62, v11
	global_store_dwordx4 v55, v[8:11], s[6:7]
	s_waitcnt vmcnt(7) lgkmcnt(1)
	v_lshlrev_b32_e32 v62, 16, v44
	v_lshlrev_b32_e32 v63, 16, v12
	v_and_b32_e32 v44, 0xffff0000, v44
	v_and_b32_e32 v12, 0xffff0000, v12
	v_mul_f32_e32 v62, v63, v62
	v_mul_f32_e32 v12, v12, v44
	v_cvt_pk_bf16_f32 v12, v62, v12
	v_lshlrev_b32_e32 v62, 16, v45
	v_lshlrev_b32_e32 v63, 16, v13
	v_and_b32_e32 v45, 0xffff0000, v45
	v_and_b32_e32 v13, 0xffff0000, v13
	v_mul_f32_e32 v62, v63, v62
	v_mul_f32_e32 v13, v13, v45
	v_cvt_pk_bf16_f32 v13, v62, v13
	v_lshlrev_b32_e32 v62, 16, v46
	v_lshlrev_b32_e32 v63, 16, v14
	v_and_b32_e32 v46, 0xffff0000, v46
	v_and_b32_e32 v14, 0xffff0000, v14
	v_mul_f32_e32 v62, v63, v62
	v_mul_f32_e32 v14, v14, v46
	v_cvt_pk_bf16_f32 v14, v62, v14
	v_lshlrev_b32_e32 v62, 16, v47
	v_lshlrev_b32_e32 v63, 16, v15
	v_and_b32_e32 v47, 0xffff0000, v47
	v_and_b32_e32 v15, 0xffff0000, v15
	v_mul_f32_e32 v62, v63, v62
	v_mul_f32_e32 v15, v15, v47
	v_cvt_pk_bf16_f32 v15, v62, v15
	global_store_dwordx4 v56, v[12:15], s[6:7]
	s_waitcnt vmcnt(7) lgkmcnt(0)
; __device__ __forceinline__ float bflo(unsigned v) { return __uint_as_float(v << 16); }
; __device__ __forceinline__ float bfhi(unsigned v) { return __uint_as_float(v & 0xffff0000u); }
; __device__ __forceinline__ void phase3(const Params& p, char* shm) {
;     ...
;         const int row = id >> 4, c = id & 15;
;         const u32x4 ov = *reinterpret_cast<const u32x4*>(shm + (row * OT_LD + c * 8) * 2);
;         const u32x4 zv = *reinterpret_cast<const u32x4*>(zsrc + (size_t)row * AW + c * 8);
;         u32x4 w;
; #pragma unroll
;         for (int q = 0; q < 4; ++q) w[q] = cvtpk(bflo(ov[q]) * bflo(zv[q]), bfhi(ov[q]) * bfhi(zv[q]));
;         *reinterpret_cast<u32x4*>(bdst + (size_t)row * AW + c * 8) = w;
;       }
	v_lshlrev_b32_e32 v62, 16, v48
	v_lshlrev_b32_e32 v63, 16, v16
	v_and_b32_e32 v48, 0xffff0000, v48
	v_and_b32_e32 v16, 0xffff0000, v16
	v_mul_f32_e32 v62, v63, v62
	v_mul_f32_e32 v16, v16, v48
	v_cvt_pk_bf16_f32 v16, v62, v16
	v_lshlrev_b32_e32 v62, 16, v49
	v_lshlrev_b32_e32 v63, 16, v17
	v_and_b32_e32 v49, 0xffff0000, v49
	v_and_b32_e32 v17, 0xffff0000, v17
	v_mul_f32_e32 v62, v63, v62
	v_mul_f32_e32 v17, v17, v49
	v_cvt_pk_bf16_f32 v17, v62, v17
	v_lshlrev_b32_e32 v62, 16, v50
	v_lshlrev_b32_e32 v63, 16, v18
	v_and_b32_e32 v50, 0xffff0000, v50
	v_and_b32_e32 v18, 0xffff0000, v18
	v_mul_f32_e32 v62, v63, v62
	v_mul_f32_e32 v18, v18, v50
	v_cvt_pk_bf16_f32 v18, v62, v18
	v_lshlrev_b32_e32 v62, 16, v51
	v_lshlrev_b32_e32 v63, 16, v19
	v_and_b32_e32 v51, 0xffff0000, v51
	v_and_b32_e32 v19, 0xffff0000, v19
	v_mul_f32_e32 v62, v63, v62
	v_mul_f32_e32 v19, v19, v51
	v_cvt_pk_bf16_f32 v19, v62, v19
	global_store_dwordx4 v57, v[16:19], s[6:7]
	ds_read_b128 v[36:39], v52 offset:34816
	ds_read_b128 v[40:43], v52 offset:43520
	ds_read_b128 v[44:47], v52 offset:52224
	ds_read_b128 v[48:51], v52 offset:60928
	s_waitcnt vmcnt(7) lgkmcnt(3)
	v_lshlrev_b32_e32 v62, 16, v36
	v_lshlrev_b32_e32 v63, 16, v20
	v_and_b32_e32 v36, 0xffff0000, v36
	v_and_b32_e32 v20, 0xffff0000, v20
	v_mul_f32_e32 v62, v63, v62
	v_mul_f32_e32 v20, v20, v36
	v_cvt_pk_bf16_f32 v20, v62, v20
	v_lshlrev_b32_e32 v62, 16, v37
	v_lshlrev_b32_e32 v63, 16, v21
	v_and_b32_e32 v37, 0xffff0000, v37
	v_and_b32_e32 v21, 0xffff0000, v21
	v_mul_f32_e32 v62, v63, v62
	v_mul_f32_e32 v21, v21, v37
	v_cvt_pk_bf16_f32 v21, v62, v21
	v_lshlrev_b32_e32 v62, 16, v38
	v_lshlrev_b32_e32 v63, 16, v22
	v_and_b32_e32 v38, 0xffff0000, v38
	v_and_b32_e32 v22, 0xffff0000, v22
	v_mul_f32_e32 v62, v63, v62
	v_mul_f32_e32 v22, v22, v38
	v_cvt_pk_bf16_f32 v22, v62, v22
	v_lshlrev_b32_e32 v62, 16, v39
	v_lshlrev_b32_e32 v63, 16, v23
	v_and_b32_e32 v39, 0xffff0000, v39
	v_and_b32_e32 v23, 0xffff0000, v23
	v_mul_f32_e32 v62, v63, v62
	v_mul_f32_e32 v23, v23, v39
	v_cvt_pk_bf16_f32 v23, v62, v23
	global_store_dwordx4 v58, v[20:23], s[6:7]
	s_waitcnt vmcnt(7) lgkmcnt(2)
	v_lshlrev_b32_e32 v62, 16, v40
	v_lshlrev_b32_e32 v63, 16, v24
	v_and_b32_e32 v40, 0xffff0000, v40
	v_and_b32_e32 v24, 0xffff0000, v24
	v_mul_f32_e32 v62, v63, v62
	v_mul_f32_e32 v24, v24, v40
	v_cvt_pk_bf16_f32 v24, v62, v24
	v_lshlrev_b32_e32 v62, 16, v41
	v_lshlrev_b32_e32 v63, 16, v25
	v_and_b32_e32 v41, 0xffff0000, v41
	v_and_b32_e32 v25, 0xffff0000, v25
	v_mul_f32_e32 v62, v63, v62
	v_mul_f32_e32 v25, v25, v41
	v_cvt_pk_bf16_f32 v25, v62, v25
	v_lshlrev_b32_e32 v62, 16, v42
	v_lshlrev_b32_e32 v63, 16, v26
	v_and_b32_e32 v42, 0xffff0000, v42
	v_and_b32_e32 v26, 0xffff0000, v26
	v_mul_f32_e32 v62, v63, v62
	v_mul_f32_e32 v26, v26, v42
	v_cvt_pk_bf16_f32 v26, v62, v26
	v_lshlrev_b32_e32 v62, 16, v43
	v_lshlrev_b32_e32 v63, 16, v27
	v_and_b32_e32 v43, 0xffff0000, v43
	v_and_b32_e32 v27, 0xffff0000, v27
	v_mul_f32_e32 v62, v63, v62
	v_mul_f32_e32 v27, v27, v43
	v_cvt_pk_bf16_f32 v27, v62, v27
	global_store_dwordx4 v59, v[24:27], s[6:7]
	s_waitcnt vmcnt(7) lgkmcnt(1)
	v_lshlrev_b32_e32 v62, 16, v44
	v_lshlrev_b32_e32 v63, 16, v28
	v_and_b32_e32 v44, 0xffff0000, v44
	v_and_b32_e32 v28, 0xffff0000, v28
	v_mul_f32_e32 v62, v63, v62
	v_mul_f32_e32 v28, v28, v44
	v_cvt_pk_bf16_f32 v28, v62, v28
	v_lshlrev_b32_e32 v62, 16, v45
	v_lshlrev_b32_e32 v63, 16, v29
	v_and_b32_e32 v45, 0xffff0000, v45
	v_and_b32_e32 v29, 0xffff0000, v29
	v_mul_f32_e32 v62, v63, v62
	v_mul_f32_e32 v29, v29, v45
	v_cvt_pk_bf16_f32 v29, v62, v29
	v_lshlrev_b32_e32 v62, 16, v46
	v_lshlrev_b32_e32 v63, 16, v30
	v_and_b32_e32 v46, 0xffff0000, v46
	v_and_b32_e32 v30, 0xffff0000, v30
	v_mul_f32_e32 v62, v63, v62
	v_mul_f32_e32 v30, v30, v46
	v_cvt_pk_bf16_f32 v30, v62, v30
	v_lshlrev_b32_e32 v62, 16, v47
	v_lshlrev_b32_e32 v63, 16, v31
	v_and_b32_e32 v47, 0xffff0000, v47
	v_and_b32_e32 v31, 0xffff0000, v31
	v_mul_f32_e32 v62, v63, v62
	v_mul_f32_e32 v31, v31, v47
	v_cvt_pk_bf16_f32 v31, v62, v31
	global_store_dwordx4 v60, v[28:31], s[6:7]
	s_waitcnt vmcnt(7) lgkmcnt(0)
	v_lshlrev_b32_e32 v62, 16, v48
	v_lshlrev_b32_e32 v63, 16, v32
	v_and_b32_e32 v48, 0xffff0000, v48
	v_and_b32_e32 v32, 0xffff0000, v32
	v_mul_f32_e32 v62, v63, v62
	v_mul_f32_e32 v32, v32, v48
	v_cvt_pk_bf16_f32 v32, v62, v32
	v_lshlrev_b32_e32 v62, 16, v49
	v_lshlrev_b32_e32 v63, 16, v33
	v_and_b32_e32 v49, 0xffff0000, v49
	v_and_b32_e32 v33, 0xffff0000, v33
	v_mul_f32_e32 v62, v63, v62
	v_mul_f32_e32 v33, v33, v49
	v_cvt_pk_bf16_f32 v33, v62, v33
	v_lshlrev_b32_e32 v62, 16, v50
	v_lshlrev_b32_e32 v63, 16, v34
	v_and_b32_e32 v50, 0xffff0000, v50
	v_and_b32_e32 v34, 0xffff0000, v34
	v_mul_f32_e32 v62, v63, v62
	v_mul_f32_e32 v34, v34, v50
	v_cvt_pk_bf16_f32 v34, v62, v34
	v_lshlrev_b32_e32 v62, 16, v51
	v_lshlrev_b32_e32 v63, 16, v35
	v_and_b32_e32 v51, 0xffff0000, v51
	v_and_b32_e32 v35, 0xffff0000, v35
	v_mul_f32_e32 v62, v63, v62
	v_mul_f32_e32 v35, v35, v51
	v_cvt_pk_bf16_f32 v35, v62, v35
	global_store_dwordx4 v61, v[32:35], s[6:7]
	v_add_u32_e32 v131, 0x1000, v131
	v_and_b32_e32 v190, 0x78, v2
	v_lshlrev_b32_e32 v190, 1, v190
	v_add_u32_e32 v2, 0x8000, v2
	s_mov_b64 s[18:19], exec
	s_nop 1
	s_branch .LBB0_322
